# DIFF attention: softmax row-sum trees rewritten from compiler-packed v_pk_add_f32 (one useful lane each) into scalar v_add_f32 chains; MLA fast path as before
# speedup vs baseline: 1.0054x; 1.0054x over previous
; template <int MODE>
; DI void attn_item(const Params& p, int layer, int bh, int qb, char* lds) {
;     ...
;   bf16x8 qf[NMAP][QS];
;   {
;     const u16* qrow = Qg + (size_t)(q0w + l32) * qstr + hh * 8;
; #pragma unroll
;     for (int mp = 0; mp < NMAP; ++mp)
; #pragma unroll
;       for (int st = 0; st < QS; ++st) qf[mp][st] = *(const bf16x8*)(qrow + (mp * QS + st) * 16);
;   }
;   f32x16 O[NMAP][2]; float m = 0.f, l[NMAP];
; #pragma unroll
;   for (int mp = 0; mp < NMAP; ++mp) {
; #pragma unroll
;     for (int r = 0; r < 16; ++r) { O[mp][0][r] = 0.f; O[mp][1][r] = 0.f; }
;     l[mp] = 0.f;
;   }
;   if (MODE == 2) { m = p.sink[layer * 6 + hd] * LOG2E; l[0] = (hh == 0) ? 1.f : 0.f; }
;   int kt0 = 0, kt1 = S / 64;
;   if (MODE == 2) { kt0 = (q0 - 128) / 64; if (kt0 < 0) kt0 = 0; kt1 = (q0 + 384) / 64; if (kt1 > S / 64) kt1 = S / 64; }
;   const int nt = kt1 - kt0;
;   constexpr int KSTRG = MODE == 0 ? 96 : 64, VSTRG = 64;
;   u32x4 rkA[KCH], rvA[1], rkB[KCH], rvB[1];
;   const __amdgpu_buffer_rsrc_t krsrc = __builtin_amdgcn_make_buffer_rsrc((void*)Kg, 0, S * KSTRG * 2, 0x00027000);
;   const __amdgpu_buffer_rsrc_t vrsrc = __builtin_amdgcn_make_buffer_rsrc((void*)Vg, 0, S * VSTRG * 2, 0x00027000);
;   auto gload = [&](int kt, u32x4 (&rk)[KCH], u32x4 (&rv)[1]) {
;     const int ksoff = kt * (64 * KSTRG * 2), vsoff = kt * (64 * VSTRG * 2);
; #pragma unroll
;     for (int i = 0; i < KCH; ++i) if (tid + NTHR * i < KCHUNKS) rk[i] = __builtin_amdgcn_raw_buffer_load_b128(krsrc, tid * 16 + NTHR * 16 * i, ksoff, 0);
;     rv[0] = __builtin_amdgcn_raw_buffer_load_b128(vrsrc, tid * 16, vsoff, 0);
;   };
;   auto lstore = [&](int st, const u32x4 (&rk)[KCH], const u32x4 (&rv)[1]) {
;     char* Ks = stage0 + st * STAGE;
; #pragma unroll
;     for (int i = 0; i < KCH; ++i) { int c = tid + NTHR * i, row = c / KCPR, ch = c % KCPR; if (c < KCHUNKS) *(u32x4*)(Ks + row * KSTR + ch * 16) = rk[i]; }
;     { int row = tid >> 3, ch = tid & 7; *(u32x4*)(Ks + KBYTES + row * VSTR + ch * 16) = rv[0]; }
;   };
;   const unsigned vlane = (unsigned)((4 * hh + ((lane & 15) >> 2)) * VSTR + 32 * ((lane >> 4) & 1) + 8 * (lane & 3));
;   bf16x8 kaug, qaug;
;   { u32x4 tk = {hh == 0 ? 0x3F803F80u : 0u, 0u, 0u, 0u}; kaug = __builtin_bit_cast(bf16x8, tk); qaug = __builtin_bit_cast(bf16x8, (u32x4){0u, 0u, 0u, 0u}); }
;     ...
;   __syncthreads();
;   gload(kt0, rkA, rvA); lstore(0, rkA, rvA);
.LBB0_403:
	s_ashr_i32 s5, s60, 5
	s_and_b32 s4, s60, 7
	s_and_b32 s5, s5, -8
	v_mov_b32_e32 v14, v184
	s_or_b32 s4, s5, s4
	s_lshl_b32 s5, s60, 5
	s_waitcnt vmcnt(0)
	v_ashrrev_i32_e32 v0, 1, v14
	s_and_b32 s5, s5, 0x1f00
	v_and_b32_e32 v0, 0xffffffe0, v0
	v_add_u32_e32 v186, s5, v0
	s_mul_hi_i32 s5, s4, 0x2aaaaaab
	s_lshr_b32 s6, s5, 31
	s_add_i32 s10, s5, s6
	s_mul_i32 s5, s10, 6
	s_sub_i32 s52, s4, s5
	s_mul_i32 s6, s10, 0x900000
	v_readlane_b32 s8, v254, 45
	s_mul_hi_i32 s5, s10, 0x900000
	v_readlane_b32 s9, v254, 46
	s_add_u32 s8, s8, s6
	s_mul_i32 s6, s52, 0x60
	s_addc_u32 s5, s9, s5
	s_ashr_i32 s7, s6, 31
	s_lshl_b64 s[6:7], s[6:7], 1
	s_add_u32 s6, s8, s6
	v_and_b32_e32 v204, 31, v14
	s_addc_u32 s7, s5, s7
	v_bfe_u32 v15, v14, 5, 1
	v_or_b32_e32 v2, v186, v204
	v_mov_b64_e32 v[0:1], s[6:7]
	s_movk_i32 s5, 0x480
	v_mad_i64_i32 v[0:1], s[6:7], v2, s5, v[0:1]
	v_lshlrev_b32_e32 v16, 4, v15
	v_mov_b32_e32 v17, v5
	v_lshl_add_u64 v[0:1], v[0:1], 0, v[16:17]
	global_load_dwordx4 v[104:107], v[0:1], off
	global_load_dwordx4 v[108:111], v[0:1], off offset:32
	global_load_dwordx4 v[112:115], v[0:1], off offset:64
	global_load_dwordx4 v[116:119], v[0:1], off offset:96
	global_load_dwordx4 v[120:123], v[0:1], off offset:128
	global_load_dwordx4 v[124:127], v[0:1], off offset:160
	s_ashr_i32 s5, s4, 31
	s_mul_hi_i32 s6, s4, 0x180000
	s_mul_i32 s7, s4, 0x180000
	s_lshl_b64 s[4:5], s[4:5], 20
	s_add_u32 s12, s68, s4
	s_addc_u32 s11, s69, s5
	s_add_u32 s20, s66, s7
	s_addc_u32 s4, s67, s6
	s_and_b32 s21, s4, 0xffff
	s_movk_i32 s4, 0x300
	v_cmp_gt_i32_e64 s[4:5], s4, v14
	v_lshlrev_b32_e32 v187, 4, v14
	v_mov_b32_e32 v100, 0
	v_mov_b32_e32 v96, 0
	v_mov_b32_e32 v97, 0
	v_mov_b32_e32 v98, 0
	v_mov_b32_e32 v99, 0
	s_barrier
	s_and_b32 s13, s11, 0xffff
	s_ashr_i32 s11, s10, 31
	s_mov_b32 s23, s15
	v_bfe_u32 v206, v184, 5, 1
	v_lshlrev_b32_e32 v206, 2, v206
	v_and_b32_e32 v196, 31, v184
	v_bfe_u32 v197, v184, 5, 1
	v_mov_b32_e32 v199, 208
	v_mul_u32_u24_e32 v200, v196, v199
	v_lshl_add_u32 v200, v197, 4, v200
	v_bfe_u32 v199, v184, 2, 2
	v_lshl_add_u32 v199, v197, 2, v199
	v_mov_b32_e32 v208, 192
	v_mul_u32_u24_e32 v201, v199, v208
	v_bfe_u32 v199, v184, 4, 1
	v_lshl_add_u32 v201, v199, 5, v201
	v_and_b32_e32 v199, 3, v184
	v_lshl_add_u32 v201, v199, 3, v201
	v_mov_b32_e32 v208, 0xaaab
	v_mul_u32_u24_e32 v196, v184, v208
	v_lshrrev_b32_e32 v196, 19, v196
	v_mul_u32_u24_e32 v197, 12, v196
	v_sub_u32_e32 v197, v184, v197
	v_mov_b32_e32 v199, 208
	v_mul_u32_u24_e32 v202, v196, v199
	v_lshl_add_u32 v202, v197, 4, v202
	v_lshrrev_b32_e32 v196, 1, v184
	v_add_u32_e32 v196, 0x200, v196
	v_mul_u32_u24_e32 v197, v196, v208
	v_lshrrev_b32_e32 v197, 19, v197
	v_mul_u32_u24_e32 v209, 12, v197
	v_sub_u32_e32 v196, v196, v209
	v_mul_u32_u24_e32 v203, v197, v199
	v_lshl_add_u32 v203, v196, 4, v203
	v_and_b32_e32 v196, 1, v184
	v_lshl_add_u32 v203, v196, 3, v203
	v_lshrrev_b32_e32 v196, 3, v184
	v_mov_b32_e32 v199, 192
	v_mul_u32_u24_e32 v207, v196, v199
	v_and_b32_e32 v196, 7, v184
	v_lshl_add_u32 v207, v196, 4, v207
	v_lshlrev_b32_e32 v187, 4, v184
	v_lshlrev_b32_e32 v205, 3, v184
	v_add_u32_e32 v205, 0x2000, v205
	v_bfe_u32 v197, v184, 5, 1
	v_cmp_eq_u32_e64 s[8:9], 0, v197
	v_mov_b32_e32 v196, 0x3f803f80
	s_nop 0
	v_cndmask_b32_e64 v240, 0, v196, s[8:9]
	v_mov_b32_e32 v241, 0
	v_mov_b32_e32 v245, 0
	v_mov_b32_e32 v242, 0
	v_mov_b32_e32 v246, 0
	v_mov_b32_e32 v243, 0
	v_mov_b32_e32 v247, 0
	buffer_load_dwordx4 v[64:67], v187, s[20:23], 0 offen
	buffer_load_dwordx2 v[68:69], v205, s[20:23], 0 offen
	buffer_load_dwordx4 v[72:75], v187, s[12:15], 0 offen
	s_movk_i32 s62, 0x3000
	buffer_load_dwordx4 v[76:79], v187, s[20:23], s62 offen
	buffer_load_dwordx2 v[80:81], v205, s[20:23], s62 offen
	s_waitcnt vmcnt(0)
	ds_write_b128 v202, v[64:67] offset:2048
	ds_write_b64 v203, v[68:69] offset:2048
	ds_write_b128 v207, v[72:75] offset:15360
	ds_write_b128 v202, v[76:79] offset:27648
	ds_write_b64 v203, v[80:81] offset:27648
	s_movk_i32 s62, 0x6000
	s_movk_i32 s29, 0x2000
	buffer_load_dwordx4 v[96:99], v187, s[20:23], s62 offen
	buffer_load_dwordx2 v[100:101], v205, s[20:23], s62 offen
	buffer_load_dwordx4 v[188:191], v187, s[12:15], s29 offen
	s_mov_b32 s62, 0x9000
	s_movk_i32 s29, 0x4000
	s_waitcnt lgkmcnt(0)
	s_barrier
	ds_read_b128 v[176:179], v200 offset:2048
	ds_read_b128 v[180:183], v200 offset:2080
	ds_read_b128 v[222:225], v200 offset:2112
	s_waitcnt lgkmcnt(2)
	v_mfma_f32_32x32x16_bf16 v[64:79], v[176:179], v[104:107], 0
	ds_read_b128 v[226:229], v200 offset:2144
	s_waitcnt lgkmcnt(2)
	v_mfma_f32_32x32x16_bf16 v[64:79], v[180:183], v[108:111], v[64:79]
	ds_read_b128 v[176:179], v200 offset:2176
	s_waitcnt lgkmcnt(2)
	v_mfma_f32_32x32x16_bf16 v[64:79], v[222:225], v[112:115], v[64:79]
	ds_read_b128 v[180:183], v200 offset:2208
	s_waitcnt lgkmcnt(2)
	v_mfma_f32_32x32x16_bf16 v[64:79], v[226:229], v[116:119], v[64:79]
	ds_read_b128 v[222:225], v200 offset:8704
	s_waitcnt lgkmcnt(2)
	v_mfma_f32_32x32x16_bf16 v[64:79], v[176:179], v[120:123], v[64:79]
	ds_read_b128 v[226:229], v200 offset:8736
	s_waitcnt lgkmcnt(2)
	v_mfma_f32_32x32x16_bf16 v[64:79], v[180:183], v[124:127], v[64:79]
	ds_read_b128 v[176:179], v200 offset:8768
	s_waitcnt lgkmcnt(2)
	v_mfma_f32_32x32x16_bf16 v[80:95], v[222:225], v[104:107], 0
	ds_read_b128 v[180:183], v200 offset:8800
	s_waitcnt lgkmcnt(2)
	v_mfma_f32_32x32x16_bf16 v[80:95], v[226:229], v[108:111], v[80:95]
	ds_read_b128 v[222:225], v200 offset:8832
	s_waitcnt lgkmcnt(2)
	v_mfma_f32_32x32x16_bf16 v[80:95], v[176:179], v[112:115], v[80:95]
	ds_read_b128 v[226:229], v200 offset:8864
	s_waitcnt lgkmcnt(2)
	v_mfma_f32_32x32x16_bf16 v[80:95], v[180:183], v[116:119], v[80:95]
	s_waitcnt lgkmcnt(1)
	v_mfma_f32_32x32x16_bf16 v[80:95], v[222:225], v[120:123], v[80:95]
	s_waitcnt lgkmcnt(0)
	v_mfma_f32_32x32x16_bf16 v[80:95], v[226:229], v[124:127], v[80:95]
	v_mov_b32_e32 v16, 0
	v_mov_b32_e32 v32, 0
	v_mov_b32_e32 v17, 0
	v_mov_b32_e32 v33, 0
	v_mov_b32_e32 v18, 0
	v_mov_b32_e32 v34, 0
	v_mov_b32_e32 v19, 0
	v_mov_b32_e32 v35, 0
	v_mov_b32_e32 v20, 0
	v_mov_b32_e32 v36, 0
	v_mov_b32_e32 v21, 0
	v_mov_b32_e32 v37, 0
	v_mov_b32_e32 v22, 0
	v_mov_b32_e32 v38, 0
	v_mov_b32_e32 v23, 0
	v_mov_b32_e32 v39, 0
	v_mov_b32_e32 v24, 0
	v_mov_b32_e32 v40, 0
	v_mov_b32_e32 v25, 0
	v_mov_b32_e32 v41, 0
	v_mov_b32_e32 v26, 0
	v_mov_b32_e32 v42, 0
	v_mov_b32_e32 v27, 0
	v_mov_b32_e32 v43, 0
	v_mov_b32_e32 v28, 0
	v_mov_b32_e32 v44, 0
	v_mov_b32_e32 v29, 0
	v_mov_b32_e32 v45, 0
	v_mov_b32_e32 v30, 0
	v_mov_b32_e32 v46, 0
	v_mov_b32_e32 v31, 0
	v_mov_b32_e32 v47, 0
	v_mov_b32_e32 v192, 0
	v_mov_b32_e32 v193, 0
	s_waitcnt lgkmcnt(0)
	s_barrier
; DI unsigned pk2(float lo, float hi) { f32x2 v = {lo, hi}; b16x2 r = __builtin_convertvector(v, b16x2); return __builtin_bit_cast(unsigned, r); }
; #define LDS_BARRIER() asm volatile("s_waitcnt lgkmcnt(0)\n\ts_barrier" ::: "memory")
; template <int MODE>
; DI void attn_item(const Params& p, int layer, int bh, int qb, char* lds) {
;     ...
;         auto rebase = [&]() {
;           float mx = fmaxf(fmaxf(s[0][0], s[0][1]), s[0][2]);
; #pragma unroll
;           for (int r = 3; r < 15; r += 2) mx = fmaxf(fmaxf(mx, s[0][r]), s[0][r + 1]);
;           mx = fmaxf(mx, s[0][15]);
; #pragma unroll
;           for (int r = 0; r < 16; r += 2) mx = fmaxf(fmaxf(mx, s[1][r]), s[1][r + 1]);
;           const float rm = xchg_max(mx);
;           float delta = first ? rm : fmaxf(rm, 0.f);
;           if (delta < -1e29f) delta = 0.f;
;           m += delta;
;           const float alpha = __builtin_amdgcn_exp2f(-delta);
; #pragma unroll
;           for (int mq = 0; mq < NMAP; ++mq) {
;             l[mq] *= alpha;
; #pragma unroll
;             for (int r = 0; r < 16; ++r) { O[mq][0][r] *= alpha; O[mq][1][r] *= alpha; }
;           }
; #pragma unroll
;           for (int r = 0; r < 16; ++r) { s[0][r] -= delta; s[1][r] -= delta; }
;           set_c0(cb - m);
;         };
;         float ps;
;         auto smpass = [&]() {
;           ps = 0.f;
; #pragma unroll
;           for (int sub = 0; sub < 2; ++sub)
; #pragma unroll
;             for (int ks = 0; ks < 2; ++ks)
; #pragma unroll
;               for (int i = 0; i < 4; ++i) {
;                 const float p0 = __builtin_amdgcn_exp2f(s[sub][8 * ks + 2 * i]), p1 = __builtin_amdgcn_exp2f(s[sub][8 * ks + 2 * i + 1]);
;                 ps += p0 + p1; pk[mp][sub][ks][i] = pk2(p0, p1);
;               }
;         };
;         if (first) rebase();
;         smpass();
;     ...
;   for (int t = 0; t < nt; t += 2) {
;     if (t + 2 < nt) gload(kt0 + t + 2, rkA, rvA);
;     compute(t, 0);
;     if (t + 1 < nt) lstore(1, rkB, rvB);
;     LDS_BARRIER();
	v_max_f32_e32 v196, v64, v65
	v_max3_f32 v196, v196, v66, v67
	v_max3_f32 v196, v196, v68, v69
	v_max3_f32 v196, v196, v70, v71
	v_max3_f32 v196, v196, v72, v73
	v_max3_f32 v196, v196, v74, v75
	v_max3_f32 v196, v196, v76, v77
	v_max3_f32 v196, v196, v78, v79
	v_max3_f32 v196, v196, v80, v81
	v_max3_f32 v196, v196, v82, v83
	v_max3_f32 v196, v196, v84, v85
	v_max3_f32 v196, v196, v86, v87
	v_max3_f32 v196, v196, v88, v89
	v_max3_f32 v196, v196, v90, v91
	v_max3_f32 v196, v196, v92, v93
	v_max3_f32 v196, v196, v94, v95
	v_mov_b32_e32 v197, v196
	s_nop 1
	v_permlane32_swap_b32_e32 v196, v197
	v_max_f32_e32 v196, v196, v197
	s_mov_b32 s24, 0xefa18f08
	v_cmp_ngt_f32_e32 vcc, s24, v196
	s_nop 1
	v_cndmask_b32_e32 v198, 0, v196, vcc
	v_sub_f32_e32 v64, v64, v198
	v_sub_f32_e32 v65, v65, v198
	v_sub_f32_e32 v66, v66, v198
	v_sub_f32_e32 v67, v67, v198
	v_sub_f32_e32 v68, v68, v198
	v_sub_f32_e32 v69, v69, v198
	v_sub_f32_e32 v70, v70, v198
	v_sub_f32_e32 v71, v71, v198
	v_sub_f32_e32 v72, v72, v198
	v_sub_f32_e32 v73, v73, v198
	v_sub_f32_e32 v74, v74, v198
	v_sub_f32_e32 v75, v75, v198
	v_sub_f32_e32 v76, v76, v198
	v_sub_f32_e32 v77, v77, v198
	v_sub_f32_e32 v78, v78, v198
	v_sub_f32_e32 v79, v79, v198
	v_sub_f32_e32 v80, v80, v198
	v_sub_f32_e32 v81, v81, v198
	v_sub_f32_e32 v82, v82, v198
	v_sub_f32_e32 v83, v83, v198
	v_sub_f32_e32 v84, v84, v198
	v_sub_f32_e32 v85, v85, v198
	v_sub_f32_e32 v86, v86, v198
	v_sub_f32_e32 v87, v87, v198
	v_sub_f32_e32 v88, v88, v198
	v_sub_f32_e32 v89, v89, v198
	v_sub_f32_e32 v90, v90, v198
	v_sub_f32_e32 v91, v91, v198
	v_sub_f32_e32 v92, v92, v198
	v_sub_f32_e32 v93, v93, v198
	v_sub_f32_e32 v94, v94, v198
	v_sub_f32_e32 v95, v95, v198
	v_sub_f32_e32 v196, 0, v198
	v_bfe_u32 v197, v196, 16, 1
	v_add3_u32 v196, v196, v197, s45
	v_lshrrev_b32_e32 v197, 16, v196
	v_and_b32_e32 v196, 0xffff0000, v196
	v_sub_f32_e64 v196, -v198, v196
	v_bfe_u32 v199, v196, 16, 1
	v_add3_u32 v196, v196, v199, s45
	v_and_or_b32 v196, v196, s92, v197
	v_cndmask_b32_e64 v244, 0, v196, s[8:9]
	s_nop 1
	v_mfma_f32_32x32x16_bf16 v[48:63], v[240:243], v[244:247], 0
	s_mov_b32 s28, 0
.Lmla_loop:
	ds_read_b128 v[176:179], v200 offset:27648
	ds_read_b128 v[180:183], v200 offset:27680
	ds_read_b128 v[222:225], v200 offset:27712
	s_waitcnt vmcnt(0)
	ds_write_b128 v202, v[96:99] offset:2048
	ds_write_b64 v203, v[100:101] offset:2048
	ds_write_b128 v207, v[188:191] offset:40960
	buffer_load_dwordx4 v[230:233], v187, s[20:23], s62 offen
	buffer_load_dwordx2 v[234:235], v205, s[20:23], s62 offen
	buffer_load_dwordx4 v[236:239], v187, s[12:15], s29 offen
	s_add_u32 s62, s62, 0x3000
	s_add_u32 s29, s29, 0x2000
	v_exp_f32_e32 v0, v64
	v_exp_f32_e32 v1, v65
	v_exp_f32_e32 v2, v66
	v_exp_f32_e32 v3, v67
	v_add_f32_e32 v10, v0, v1
	v_cvt_pk_bf16_f32 v160, v0, v1
	s_waitcnt lgkmcnt(5)
	v_mfma_f32_32x32x16_bf16 v[128:143], v[176:179], v[104:107], v[48:63]
	ds_read_b128 v[226:229], v200 offset:27744
	s_waitcnt lgkmcnt(5)
	v_mfma_f32_32x32x16_bf16 v[128:143], v[180:183], v[108:111], v[128:143]
	ds_read_b64_tr_b16 v[176:177], v201 offset:15360
	ds_read_b64_tr_b16 v[178:179], v201 offset:16896
	v_add_f32_e32 v10, v10, v2
	v_add_f32_e32 v10, v10, v3
	v_cvt_pk_bf16_f32 v161, v2, v3
	s_waitcnt lgkmcnt(6)
	v_mfma_f32_32x32x16_bf16 v[128:143], v[222:225], v[112:115], v[128:143]
	ds_read_b64_tr_b16 v[180:181], v201 offset:15424
	ds_read_b64_tr_b16 v[182:183], v201 offset:16960
	v_exp_f32_e32 v6, v68
	v_exp_f32_e32 v7, v69
	v_exp_f32_e32 v8, v70
	v_exp_f32_e32 v9, v71
	v_add_f32_e32 v10, v10, v6
	s_waitcnt lgkmcnt(4)
	v_mfma_f32_32x32x16_bf16 v[128:143], v[226:229], v[116:119], v[128:143]
	ds_read_b128 v[222:225], v200 offset:27776
	v_add_f32_e32 v10, v10, v7
	v_cvt_pk_bf16_f32 v162, v6, v7
	v_add_f32_e32 v10, v10, v8
	v_add_f32_e32 v10, v10, v9
	v_cvt_pk_bf16_f32 v163, v8, v9
	s_waitcnt lgkmcnt(3)
	s_nop 0
	v_mfma_f32_32x32x16_bf16 v[32:47], v[176:179], v[160:163], v[32:47]
	ds_read_b128 v[226:229], v200 offset:27808
	v_exp_f32_e32 v0, v72
	v_exp_f32_e32 v1, v73
	v_exp_f32_e32 v2, v74
	s_waitcnt lgkmcnt(2)
	v_mfma_f32_32x32x16_bf16 v[16:31], v[180:183], v[160:163], v[16:31]
	ds_read_b128 v[176:179], v200 offset:34304
	v_exp_f32_e32 v3, v75
	v_add_f32_e32 v11, v0, v1
	v_cvt_pk_bf16_f32 v164, v0, v1
	v_add_f32_e32 v11, v11, v2
	s_waitcnt lgkmcnt(2)
	v_mfma_f32_32x32x16_bf16 v[128:143], v[222:225], v[120:123], v[128:143]
	ds_read_b64_tr_b16 v[180:181], v201 offset:18432
	ds_read_b64_tr_b16 v[182:183], v201 offset:19968
	v_add_f32_e32 v11, v11, v3
	v_cvt_pk_bf16_f32 v165, v2, v3
	v_exp_f32_e32 v6, v76
	v_exp_f32_e32 v7, v77
	s_waitcnt lgkmcnt(3)
	v_mfma_f32_32x32x16_bf16 v[128:143], v[226:229], v[124:127], v[128:143]
	ds_read_b64_tr_b16 v[222:223], v201 offset:18496
	ds_read_b64_tr_b16 v[224:225], v201 offset:20032
	v_exp_f32_e32 v8, v78
	v_exp_f32_e32 v9, v79
	v_add_f32_e32 v11, v11, v6
	v_add_f32_e32 v11, v11, v7
	s_waitcnt lgkmcnt(4)
	v_mfma_f32_32x32x16_bf16 v[144:159], v[176:179], v[104:107], v[48:63]
	ds_read_b128 v[226:229], v200 offset:34336
	v_cvt_pk_bf16_f32 v166, v6, v7
	v_add_f32_e32 v11, v11, v8
	v_add_f32_e32 v11, v11, v9
	v_cvt_pk_bf16_f32 v167, v8, v9
	s_waitcnt lgkmcnt(3)
	s_nop 0
	v_mfma_f32_32x32x16_bf16 v[32:47], v[180:183], v[164:167], v[32:47]
	ds_read_b128 v[176:179], v200 offset:34368
	v_exp_f32_e32 v0, v80
	v_exp_f32_e32 v1, v81
	v_exp_f32_e32 v2, v82
	s_waitcnt lgkmcnt(2)
	v_mfma_f32_32x32x16_bf16 v[16:31], v[222:225], v[164:167], v[16:31]
	ds_read_b128 v[180:183], v200 offset:34400
	v_exp_f32_e32 v3, v83
	v_add_f32_e32 v12, v0, v1
	v_cvt_pk_bf16_f32 v168, v0, v1
	v_add_f32_e32 v12, v12, v2
	s_waitcnt lgkmcnt(2)
; #define MFMA(a, b, c) __builtin_amdgcn_mfma_f32_32x32x16_bf16((a), (b), (c), 0, 0, 0)
; DI unsigned pk2(float lo, float hi) { f32x2 v = {lo, hi}; b16x2 r = __builtin_convertvector(v, b16x2); return __builtin_bit_cast(unsigned, r); }
; template <int MODE>
; DI void attn_item(const Params& p, int layer, int bh, int qb, char* lds) {
;     ...
;         auto smpass = [&]() {
;           ps = 0.f;
; #pragma unroll
;           for (int sub = 0; sub < 2; ++sub)
; #pragma unroll
;             for (int ks = 0; ks < 2; ++ks)
; #pragma unroll
;               for (int i = 0; i < 4; ++i) {
;                 const float p0 = __builtin_amdgcn_exp2f(s[sub][8 * ks + 2 * i]), p1 = __builtin_amdgcn_exp2f(s[sub][8 * ks + 2 * i + 1]);
;                 ps += p0 + p1; pk[mp][sub][ks][i] = pk2(p0, p1);
;               }
;         };
;         if (first) rebase();
;         smpass();
;         if (!first && __any(!(ps <= PSLIM))) { rebase(); smpass(); }
;         l[mp] += ps;
;         __builtin_amdgcn_sched_barrier(0);
;       }
; #pragma unroll
;       for (int sub = 0; sub < 2; ++sub) {
;         s16x4 vv[8];
;         if (NMAP == 1) {
; #pragma unroll
;           for (int i = 0; i < 8; ++i) vv[i] = vpre[sub * 8 + i];
;         } else {
;           if (sub == 0) trread8<0>(vaddr, vv); else trread8<32 * VSTR>(vaddr, vv);
;         }
;         __builtin_amdgcn_s_setprio(1);
; #pragma unroll
;         for (int ks = 0; ks < 2; ++ks) {
; #pragma unroll
;           for (int dt = 0; dt < 2; ++dt) {
;             s16x4 lo = vv[ks * 4 + dt * 2], hi = vv[ks * 4 + dt * 2 + 1];
;             bf16x8 vf = __builtin_shufflevector(lo, hi, 0, 1, 2, 3, 4, 5, 6, 7);
; #pragma unroll
;             for (int mp = 0; mp < NMAP; ++mp) O[mp][dt] = MFMA(vf, __builtin_bit_cast(bf16x8, pk[mp][sub][ks]), O[mp][dt]);
;           }
;         }
;         __builtin_amdgcn_s_setprio(0);
;         __builtin_amdgcn_sched_barrier(0);
;       }
	v_mfma_f32_32x32x16_bf16 v[144:159], v[226:229], v[108:111], v[144:159]
	ds_read_b64_tr_b16 v[222:223], v201 offset:21504
	ds_read_b64_tr_b16 v[224:225], v201 offset:23040
	v_add_f32_e32 v12, v12, v3
	v_cvt_pk_bf16_f32 v169, v2, v3
	v_exp_f32_e32 v6, v84
	v_exp_f32_e32 v7, v85
	s_waitcnt lgkmcnt(3)
	v_mfma_f32_32x32x16_bf16 v[144:159], v[176:179], v[112:115], v[144:159]
	ds_read_b64_tr_b16 v[226:227], v201 offset:21568
	ds_read_b64_tr_b16 v[228:229], v201 offset:23104
	v_exp_f32_e32 v8, v86
	v_exp_f32_e32 v9, v87
	v_add_f32_e32 v12, v12, v6
	v_add_f32_e32 v12, v12, v7
	s_waitcnt lgkmcnt(4)
	v_mfma_f32_32x32x16_bf16 v[144:159], v[180:183], v[116:119], v[144:159]
	ds_read_b128 v[176:179], v200 offset:34432
	v_cvt_pk_bf16_f32 v170, v6, v7
	v_add_f32_e32 v12, v12, v8
	v_add_f32_e32 v12, v12, v9
	v_cvt_pk_bf16_f32 v171, v8, v9
	s_waitcnt lgkmcnt(3)
	s_nop 0
	v_mfma_f32_32x32x16_bf16 v[32:47], v[222:225], v[168:171], v[32:47]
	ds_read_b128 v[180:183], v200 offset:34464
	v_exp_f32_e32 v0, v88
	v_exp_f32_e32 v1, v89
	v_exp_f32_e32 v2, v90
	v_exp_f32_e32 v3, v91
	s_waitcnt lgkmcnt(2)
	v_mfma_f32_32x32x16_bf16 v[16:31], v[226:229], v[168:171], v[16:31]
	ds_read_b64_tr_b16 v[222:223], v201 offset:24576
	ds_read_b64_tr_b16 v[224:225], v201 offset:26112
	v_add_f32_e32 v13, v0, v1
	v_cvt_pk_bf16_f32 v172, v0, v1
	v_add_f32_e32 v13, v13, v2
	v_add_f32_e32 v13, v13, v3
	v_cvt_pk_bf16_f32 v173, v2, v3
	s_waitcnt lgkmcnt(3)
	v_mfma_f32_32x32x16_bf16 v[144:159], v[176:179], v[120:123], v[144:159]
	ds_read_b64_tr_b16 v[226:227], v201 offset:24640
	ds_read_b64_tr_b16 v[228:229], v201 offset:26176
	v_exp_f32_e32 v6, v92
	v_exp_f32_e32 v7, v93
	v_exp_f32_e32 v8, v94
	v_exp_f32_e32 v9, v95
	v_add_f32_e32 v13, v13, v6
	s_waitcnt lgkmcnt(4)
	v_mfma_f32_32x32x16_bf16 v[144:159], v[180:183], v[124:127], v[144:159]
	v_add_f32_e32 v13, v13, v7
	v_cvt_pk_bf16_f32 v174, v6, v7
	v_add_f32_e32 v13, v13, v8
	v_add_f32_e32 v13, v13, v9
	v_cvt_pk_bf16_f32 v175, v8, v9
	s_waitcnt lgkmcnt(2)
	s_nop 0
	v_mfma_f32_32x32x16_bf16 v[32:47], v[222:225], v[172:175], v[32:47]
	s_waitcnt lgkmcnt(0)
	v_mfma_f32_32x32x16_bf16 v[16:31], v[226:229], v[172:175], v[16:31]
	v_add_f32_e32 v10, v10, v11
	v_add_f32_e32 v12, v12, v13
	v_add_f32_e32 v10, v10, v12
	v_add_f32_e32 v192, v192, v10
	v_max_f32_e32 v193, v193, v10
	s_waitcnt lgkmcnt(0)
	s_barrier
; #define MFMA(a, b, c) __builtin_amdgcn_mfma_f32_32x32x16_bf16((a), (b), (c), 0, 0, 0)
; #define LDS_BARRIER() asm volatile("s_waitcnt lgkmcnt(0)\n\ts_barrier" ::: "memory")
; template <int MODE>
; DI void attn_item(const Params& p, int layer, int bh, int qb, char* lds) {
;     ...
;         auto smpass = [&]() {
;           ps = 0.f;
; #pragma unroll
;           for (int sub = 0; sub < 2; ++sub)
; #pragma unroll
;             for (int ks = 0; ks < 2; ++ks)
; #pragma unroll
;               for (int i = 0; i < 4; ++i) {
;                 const float p0 = __builtin_amdgcn_exp2f(s[sub][8 * ks + 2 * i]), p1 = __builtin_amdgcn_exp2f(s[sub][8 * ks + 2 * i + 1]);
;                 ps += p0 + p1; pk[mp][sub][ks][i] = pk2(p0, p1);
;               }
;         };
;         if (first) rebase();
;         smpass();
;         if (!first && __any(!(ps <= PSLIM))) { rebase(); smpass(); }
;         l[mp] += ps;
;         __builtin_amdgcn_sched_barrier(0);
;       }
; #pragma unroll
;       for (int sub = 0; sub < 2; ++sub) {
;         s16x4 vv[8];
;         if (NMAP == 1) {
; #pragma unroll
;           for (int i = 0; i < 8; ++i) vv[i] = vpre[sub * 8 + i];
;         } else {
;           if (sub == 0) trread8<0>(vaddr, vv); else trread8<32 * VSTR>(vaddr, vv);
;         }
;         __builtin_amdgcn_s_setprio(1);
; #pragma unroll
;         for (int ks = 0; ks < 2; ++ks) {
; #pragma unroll
;           for (int dt = 0; dt < 2; ++dt) {
;             s16x4 lo = vv[ks * 4 + dt * 2], hi = vv[ks * 4 + dt * 2 + 1];
;             bf16x8 vf = __builtin_shufflevector(lo, hi, 0, 1, 2, 3, 4, 5, 6, 7);
; #pragma unroll
;             for (int mp = 0; mp < NMAP; ++mp) O[mp][dt] = MFMA(vf, __builtin_bit_cast(bf16x8, pk[mp][sub][ks]), O[mp][dt]);
;           }
;         }
;         __builtin_amdgcn_s_setprio(0);
;         __builtin_amdgcn_sched_barrier(0);
;       }
;     }
;   };
;   __syncthreads();
;   gload(kt0, rkA, rvA); lstore(0, rkA, rvA);
;   if (nt > 1) gload(kt0 + 1, rkB, rvB);
;   LDS_BARRIER();
;   for (int t = 0; t < nt; t += 2) {
;     if (t + 2 < nt) gload(kt0 + t + 2, rkA, rvA);
;     compute(t, 0);
;     if (t + 1 < nt) lstore(1, rkB, rvB);
;     LDS_BARRIER();
;     if (t + 1 >= nt) break;
;     if (t + 3 < nt) gload(kt0 + t + 3, rkB, rvB);
;     compute(t + 1, 1);
;     if (t + 2 < nt) lstore(0, rkA, rvA);
;     LDS_BARRIER();
	ds_read_b128 v[176:179], v200 offset:2048
	ds_read_b128 v[180:183], v200 offset:2080
	ds_read_b128 v[222:225], v200 offset:2112
	s_waitcnt vmcnt(0)
	ds_write_b128 v202, v[230:233] offset:27648
	ds_write_b64 v203, v[234:235] offset:27648
	ds_write_b128 v207, v[236:239] offset:15360
	buffer_load_dwordx4 v[96:99], v187, s[20:23], s62 offen
	buffer_load_dwordx2 v[100:101], v205, s[20:23], s62 offen
	buffer_load_dwordx4 v[188:191], v187, s[12:15], s29 offen
	s_add_u32 s62, s62, 0x3000
	s_add_u32 s29, s29, 0x2000
	v_exp_f32_e32 v0, v128
	v_exp_f32_e32 v1, v129
	v_exp_f32_e32 v2, v130
	v_exp_f32_e32 v3, v131
	v_add_f32_e32 v10, v0, v1
	v_cvt_pk_bf16_f32 v160, v0, v1
	s_waitcnt lgkmcnt(5)
	v_mfma_f32_32x32x16_bf16 v[64:79], v[176:179], v[104:107], v[48:63]
	ds_read_b128 v[226:229], v200 offset:2144
	s_waitcnt lgkmcnt(5)
	v_mfma_f32_32x32x16_bf16 v[64:79], v[180:183], v[108:111], v[64:79]
	ds_read_b64_tr_b16 v[176:177], v201 offset:40960
	ds_read_b64_tr_b16 v[178:179], v201 offset:42496
	v_add_f32_e32 v10, v10, v2
	v_add_f32_e32 v10, v10, v3
	v_cvt_pk_bf16_f32 v161, v2, v3
	s_waitcnt lgkmcnt(6)
	v_mfma_f32_32x32x16_bf16 v[64:79], v[222:225], v[112:115], v[64:79]
	ds_read_b64_tr_b16 v[180:181], v201 offset:41024
	ds_read_b64_tr_b16 v[182:183], v201 offset:42560
	v_exp_f32_e32 v6, v132
	v_exp_f32_e32 v7, v133
	v_exp_f32_e32 v8, v134
	v_exp_f32_e32 v9, v135
	v_add_f32_e32 v10, v10, v6
	s_waitcnt lgkmcnt(4)
	v_mfma_f32_32x32x16_bf16 v[64:79], v[226:229], v[116:119], v[64:79]
	ds_read_b128 v[222:225], v200 offset:2176
	v_add_f32_e32 v10, v10, v7
	v_cvt_pk_bf16_f32 v162, v6, v7
	v_add_f32_e32 v10, v10, v8
	v_add_f32_e32 v10, v10, v9
	v_cvt_pk_bf16_f32 v163, v8, v9
	s_waitcnt lgkmcnt(3)
	s_nop 0
	v_mfma_f32_32x32x16_bf16 v[32:47], v[176:179], v[160:163], v[32:47]
	ds_read_b128 v[226:229], v200 offset:2208
	v_exp_f32_e32 v0, v136
	v_exp_f32_e32 v1, v137
	v_exp_f32_e32 v2, v138
	s_waitcnt lgkmcnt(2)
	v_mfma_f32_32x32x16_bf16 v[16:31], v[180:183], v[160:163], v[16:31]
	ds_read_b128 v[176:179], v200 offset:8704
	v_exp_f32_e32 v3, v139
	v_add_f32_e32 v11, v0, v1
	v_cvt_pk_bf16_f32 v164, v0, v1
	v_add_f32_e32 v11, v11, v2
	s_waitcnt lgkmcnt(2)
	v_mfma_f32_32x32x16_bf16 v[64:79], v[222:225], v[120:123], v[64:79]
	ds_read_b64_tr_b16 v[180:181], v201 offset:44032
	ds_read_b64_tr_b16 v[182:183], v201 offset:45568
	v_add_f32_e32 v11, v11, v3
	v_cvt_pk_bf16_f32 v165, v2, v3
	v_exp_f32_e32 v6, v140
	v_exp_f32_e32 v7, v141
	s_waitcnt lgkmcnt(3)
	v_mfma_f32_32x32x16_bf16 v[64:79], v[226:229], v[124:127], v[64:79]
	ds_read_b64_tr_b16 v[222:223], v201 offset:44096
	ds_read_b64_tr_b16 v[224:225], v201 offset:45632
	v_exp_f32_e32 v8, v142
	v_exp_f32_e32 v9, v143
	v_add_f32_e32 v11, v11, v6
	v_add_f32_e32 v11, v11, v7
	s_waitcnt lgkmcnt(4)
	v_mfma_f32_32x32x16_bf16 v[80:95], v[176:179], v[104:107], v[48:63]
	ds_read_b128 v[226:229], v200 offset:8736
	v_cvt_pk_bf16_f32 v166, v6, v7
	v_add_f32_e32 v11, v11, v8
	v_add_f32_e32 v11, v11, v9
	v_cvt_pk_bf16_f32 v167, v8, v9
	s_waitcnt lgkmcnt(3)
	s_nop 0
	v_mfma_f32_32x32x16_bf16 v[32:47], v[180:183], v[164:167], v[32:47]
	ds_read_b128 v[176:179], v200 offset:8768
	v_exp_f32_e32 v0, v144
	v_exp_f32_e32 v1, v145
	v_exp_f32_e32 v2, v146
	s_waitcnt lgkmcnt(2)
	v_mfma_f32_32x32x16_bf16 v[16:31], v[222:225], v[164:167], v[16:31]
	ds_read_b128 v[180:183], v200 offset:8800
	v_exp_f32_e32 v3, v147
	v_add_f32_e32 v12, v0, v1
	v_cvt_pk_bf16_f32 v168, v0, v1
	v_add_f32_e32 v12, v12, v2
	s_waitcnt lgkmcnt(2)
	v_mfma_f32_32x32x16_bf16 v[80:95], v[226:229], v[108:111], v[80:95]
	ds_read_b64_tr_b16 v[222:223], v201 offset:47104
	ds_read_b64_tr_b16 v[224:225], v201 offset:48640
	v_add_f32_e32 v12, v12, v3
	v_cvt_pk_bf16_f32 v169, v2, v3
	v_exp_f32_e32 v6, v148
	v_exp_f32_e32 v7, v149
	s_waitcnt lgkmcnt(3)
	v_mfma_f32_32x32x16_bf16 v[80:95], v[176:179], v[112:115], v[80:95]
	ds_read_b64_tr_b16 v[226:227], v201 offset:47168
	ds_read_b64_tr_b16 v[228:229], v201 offset:48704
	v_exp_f32_e32 v8, v150
	v_exp_f32_e32 v9, v151
	v_add_f32_e32 v12, v12, v6
	v_add_f32_e32 v12, v12, v7
	s_waitcnt lgkmcnt(4)
	v_mfma_f32_32x32x16_bf16 v[80:95], v[180:183], v[116:119], v[80:95]
	ds_read_b128 v[176:179], v200 offset:8832
	v_cvt_pk_bf16_f32 v170, v6, v7
	v_add_f32_e32 v12, v12, v8
	v_add_f32_e32 v12, v12, v9
	v_cvt_pk_bf16_f32 v171, v8, v9
	s_waitcnt lgkmcnt(3)
	s_nop 0
	v_mfma_f32_32x32x16_bf16 v[32:47], v[222:225], v[168:171], v[32:47]
	ds_read_b128 v[180:183], v200 offset:8864
	v_exp_f32_e32 v0, v152
	v_exp_f32_e32 v1, v153
	v_exp_f32_e32 v2, v154
	v_exp_f32_e32 v3, v155
	s_waitcnt lgkmcnt(2)
	v_mfma_f32_32x32x16_bf16 v[16:31], v[226:229], v[168:171], v[16:31]
	ds_read_b64_tr_b16 v[222:223], v201 offset:50176
	ds_read_b64_tr_b16 v[224:225], v201 offset:51712
	v_add_f32_e32 v13, v0, v1
	v_cvt_pk_bf16_f32 v172, v0, v1
	v_add_f32_e32 v13, v13, v2
	v_add_f32_e32 v13, v13, v3
	v_cvt_pk_bf16_f32 v173, v2, v3
	s_waitcnt lgkmcnt(3)
	v_mfma_f32_32x32x16_bf16 v[80:95], v[176:179], v[120:123], v[80:95]
	ds_read_b64_tr_b16 v[226:227], v201 offset:50240
	ds_read_b64_tr_b16 v[228:229], v201 offset:51776
	v_exp_f32_e32 v6, v156
	v_exp_f32_e32 v7, v157
	v_exp_f32_e32 v8, v158
	v_exp_f32_e32 v9, v159
	v_add_f32_e32 v13, v13, v6
	s_waitcnt lgkmcnt(4)
	v_mfma_f32_32x32x16_bf16 v[80:95], v[180:183], v[124:127], v[80:95]
	v_add_f32_e32 v13, v13, v7
	v_cvt_pk_bf16_f32 v174, v6, v7
	v_add_f32_e32 v13, v13, v8
	v_add_f32_e32 v13, v13, v9
	v_cvt_pk_bf16_f32 v175, v8, v9
	s_waitcnt lgkmcnt(2)
	s_nop 0
	v_mfma_f32_32x32x16_bf16 v[32:47], v[222:225], v[172:175], v[32:47]
	s_waitcnt lgkmcnt(0)
	v_mfma_f32_32x32x16_bf16 v[16:31], v[226:229], v[172:175], v[16:31]
	v_add_f32_e32 v10, v10, v11
	v_add_f32_e32 v12, v12, v13
	v_add_f32_e32 v10, v10, v12
	v_add_f32_e32 v192, v192, v10
	v_max_f32_e32 v193, v193, v10
	s_add_u32 s28, s28, 2
	s_cmpk_lt_u32 s28, 0x80
	s_waitcnt lgkmcnt(0)
	s_barrier
	s_cbranch_scc1 .Lmla_loop
	s_waitcnt vmcnt(0)
	v_cmp_nge_f32_e32 vcc, s94, v193
	s_nop 0
	s_cmp_lg_u64 vcc, 0
	s_cselect_b32 s24, 1, 0
	v_mov_b32_e32 v196, s24
	v_lshrrev_b32_e32 v197, 6, v184
	v_lshlrev_b32_e32 v197, 2, v197
	ds_write_b32 v197, v196 offset:0
	s_waitcnt lgkmcnt(0)
	s_barrier
	v_mov_b32_e32 v197, 0
	ds_read_b128 v[0:3], v197 offset:0
	ds_read_b128 v[6:9], v197 offset:16
	s_waitcnt lgkmcnt(0)
	v_or3_b32 v196, v0, v1, v2
	v_or3_b32 v196, v196, v3, v6
	v_or3_b32 v196, v196, v7, v8
	v_or_b32_e32 v196, v196, v9
	s_nop 0
	v_readfirstlane_b32 s24, v196
	s_nop 0
	s_cmp_lg_u32 s24, 0
	s_cbranch_scc1 .Lmla_slow
	s_branch .LBB0_320

; DI unsigned pk2(float lo, float hi) { f32x2 v = {lo, hi}; b16x2 r = __builtin_convertvector(v, b16x2); return __builtin_bit_cast(unsigned, r); }
; template <int MODE>
; DI void attn_item(const Params& p, int layer, int bh, int qb, char* lds) {
;     ...
;         auto smpass = [&]() {
;           ps = 0.f;
; #pragma unroll
;           for (int sub = 0; sub < 2; ++sub)
; #pragma unroll
;             for (int ks = 0; ks < 2; ++ks)
; #pragma unroll
;               for (int i = 0; i < 4; ++i) {
;                 const float p0 = __builtin_amdgcn_exp2f(s[sub][8 * ks + 2 * i]), p1 = __builtin_amdgcn_exp2f(s[sub][8 * ks + 2 * i + 1]);
;                 ps += p0 + p1; pk[mp][sub][ks][i] = pk2(p0, p1);
;               }
;         };
;         if (first) rebase();
;         smpass();
;         if (!first && __any(!(ps <= PSLIM))) { rebase(); smpass(); }
.LBB0_472:
	v_exp_f32_e32 v6, v88
	v_exp_f32_e32 v7, v89
	v_exp_f32_e32 v172, v90
	v_exp_f32_e32 v173, v91
	v_add_f32_e32 v4, v6, v7
	v_cvt_pk_bf16_f32 v152, v6, v7
	v_add_f32_e32 v4, v4, v172
	v_add_f32_e32 v4, v4, v173
	v_cvt_pk_bf16_f32 v153, v172, v173
	v_exp_f32_e32 v174, v92
	v_exp_f32_e32 v175, v93
	v_exp_f32_e32 v6, v94
	v_exp_f32_e32 v7, v95
	v_add_f32_e32 v4, v4, v174
	v_add_f32_e32 v4, v4, v175
	v_cvt_pk_bf16_f32 v154, v174, v175
	v_add_f32_e32 v4, v4, v6
	v_add_f32_e32 v4, v4, v7
	v_cvt_pk_bf16_f32 v155, v6, v7
	v_exp_f32_e32 v172, v96
	v_exp_f32_e32 v173, v97
	v_exp_f32_e32 v174, v98
	v_exp_f32_e32 v175, v99
	v_add_f32_e32 v4, v4, v172
	v_add_f32_e32 v4, v4, v173
	v_cvt_pk_bf16_f32 v156, v172, v173
	v_add_f32_e32 v4, v4, v174
	v_add_f32_e32 v4, v4, v175
	v_cvt_pk_bf16_f32 v157, v174, v175
	v_exp_f32_e32 v6, v100
	v_exp_f32_e32 v7, v101
	v_exp_f32_e32 v172, v102
	v_exp_f32_e32 v173, v103
	v_add_f32_e32 v4, v4, v6
	v_add_f32_e32 v4, v4, v7
	v_cvt_pk_bf16_f32 v158, v6, v7
	v_add_f32_e32 v4, v4, v172
	v_add_f32_e32 v4, v4, v173
	v_cvt_pk_bf16_f32 v159, v172, v173
	v_exp_f32_e32 v174, v104
	v_exp_f32_e32 v175, v105
	v_exp_f32_e32 v6, v106
	v_exp_f32_e32 v7, v107
	v_add_f32_e32 v4, v4, v174
	v_add_f32_e32 v4, v4, v175
	v_cvt_pk_bf16_f32 v160, v174, v175
	v_add_f32_e32 v4, v4, v6
	v_add_f32_e32 v4, v4, v7
	v_cvt_pk_bf16_f32 v161, v6, v7
	v_exp_f32_e32 v172, v108
	v_exp_f32_e32 v173, v109
	v_exp_f32_e32 v174, v110
	v_exp_f32_e32 v175, v111
	v_add_f32_e32 v4, v4, v172
	v_add_f32_e32 v4, v4, v173
	v_cvt_pk_bf16_f32 v162, v172, v173
	v_add_f32_e32 v4, v4, v174
	v_add_f32_e32 v4, v4, v175
	v_cvt_pk_bf16_f32 v163, v174, v175
	v_exp_f32_e32 v6, v112
	v_exp_f32_e32 v7, v113
	v_exp_f32_e32 v172, v114
	v_exp_f32_e32 v173, v115
	v_add_f32_e32 v4, v4, v6
	v_add_f32_e32 v4, v4, v7
	v_cvt_pk_bf16_f32 v164, v6, v7
	v_add_f32_e32 v4, v4, v172
	v_add_f32_e32 v4, v4, v173
	v_cvt_pk_bf16_f32 v165, v172, v173
	v_exp_f32_e32 v174, v116
	v_exp_f32_e32 v175, v117
	v_exp_f32_e32 v6, v118
	v_exp_f32_e32 v7, v119
	v_add_f32_e32 v4, v4, v174
	v_add_f32_e32 v4, v4, v175
	v_cvt_pk_bf16_f32 v166, v174, v175
	v_add_f32_e32 v4, v4, v6
	v_add_f32_e32 v4, v4, v7
	v_cvt_pk_bf16_f32 v167, v6, v7
	s_andn2_b64 vcc, exec, s[26:27]
	s_cbranch_vccnz .LBB0_475
	v_cmp_nge_f32_e32 vcc, s94, v4
	s_cbranch_vccz .LBB0_475
; DI unsigned pk2(float lo, float hi) { f32x2 v = {lo, hi}; b16x2 r = __builtin_convertvector(v, b16x2); return __builtin_bit_cast(unsigned, r); }
; template <int MODE>
; DI void attn_item(const Params& p, int layer, int bh, int qb, char* lds) {
;     ...
;         auto rebase = [&]() {
;           float mx = fmaxf(fmaxf(s[0][0], s[0][1]), s[0][2]);
; #pragma unroll
;           for (int r = 3; r < 15; r += 2) mx = fmaxf(fmaxf(mx, s[0][r]), s[0][r + 1]);
;           mx = fmaxf(mx, s[0][15]);
; #pragma unroll
;           for (int r = 0; r < 16; r += 2) mx = fmaxf(fmaxf(mx, s[1][r]), s[1][r + 1]);
;           const float rm = xchg_max(mx);
;           float delta = first ? rm : fmaxf(rm, 0.f);
;           if (delta < -1e29f) delta = 0.f;
;           m += delta;
;           const float alpha = __builtin_amdgcn_exp2f(-delta);
; #pragma unroll
;           for (int mq = 0; mq < NMAP; ++mq) {
;             l[mq] *= alpha;
; #pragma unroll
;             for (int r = 0; r < 16; ++r) { O[mq][0][r] *= alpha; O[mq][1][r] *= alpha; }
;           }
; #pragma unroll
;           for (int r = 0; r < 16; ++r) { s[0][r] -= delta; s[1][r] -= delta; }
;           set_c0(cb - m);
;         };
;         float ps;
;         auto smpass = [&]() {
;           ps = 0.f;
; #pragma unroll
;           for (int sub = 0; sub < 2; ++sub)
; #pragma unroll
;             for (int ks = 0; ks < 2; ++ks)
; #pragma unroll
;               for (int i = 0; i < 4; ++i) {
;                 const float p0 = __builtin_amdgcn_exp2f(s[sub][8 * ks + 2 * i]), p1 = __builtin_amdgcn_exp2f(s[sub][8 * ks + 2 * i + 1]);
;                 ps += p0 + p1; pk[mp][sub][ks][i] = pk2(p0, p1);
;               }
;         };
;         if (first) rebase();
;         smpass();
;         if (!first && __any(!(ps <= PSLIM))) { rebase(); smpass(); }
	v_max_f32_e32 v4, v89, v89
	v_max_f32_e32 v6, v88, v88
	v_max_f32_e32 v4, v6, v4
	v_max3_f32 v4, v4, v90, v91
	v_max3_f32 v4, v4, v92, v93
	v_max3_f32 v4, v4, v94, v95
	v_max3_f32 v4, v4, v96, v97
	v_max3_f32 v4, v4, v98, v99
	v_max3_f32 v4, v4, v100, v101
	v_max3_f32 v4, v4, v102, v103
	v_max3_f32 v4, v4, v104, v105
	v_max3_f32 v4, v4, v106, v107
	v_max3_f32 v4, v4, v108, v109
	v_max3_f32 v4, v4, v110, v111
	v_max3_f32 v4, v4, v112, v113
	v_max3_f32 v4, v4, v114, v115
	v_max3_f32 v4, v4, v116, v117
	v_max3_f32 v4, v4, v118, v119
	v_mov_b32_e32 v6, v4
	s_nop 1
	v_permlane32_swap_b32_e32 v4, v6
	v_max3_f32 v6, v4, v6, 0
	v_exp_f32_e64 v4, -v6
	v_add_f32_e32 v211, v211, v6
	v_sub_f32_e32 v88, v88, v6
	v_sub_f32_e32 v104, v104, v6
	v_pk_mul_f32 v[70:71], v[70:71], v[4:5] op_sel_hi:[1,0]
	v_pk_mul_f32 v[68:69], v[68:69], v[4:5] op_sel_hi:[1,0]
	v_pk_mul_f32 v[66:67], v[66:67], v[4:5] op_sel_hi:[1,0]
	v_pk_mul_f32 v[64:65], v[64:65], v[4:5] op_sel_hi:[1,0]
	v_pk_mul_f32 v[62:63], v[62:63], v[4:5] op_sel_hi:[1,0]
	v_pk_mul_f32 v[60:61], v[60:61], v[4:5] op_sel_hi:[1,0]
	v_pk_mul_f32 v[58:59], v[58:59], v[4:5] op_sel_hi:[1,0]
	v_pk_mul_f32 v[56:57], v[56:57], v[4:5] op_sel_hi:[1,0]
	v_pk_mul_f32 v[38:39], v[38:39], v[4:5] op_sel_hi:[1,0]
	v_pk_mul_f32 v[36:37], v[36:37], v[4:5] op_sel_hi:[1,0]
	v_pk_mul_f32 v[34:35], v[34:35], v[4:5] op_sel_hi:[1,0]
	v_pk_mul_f32 v[32:33], v[32:33], v[4:5] op_sel_hi:[1,0]
	v_pk_mul_f32 v[30:31], v[30:31], v[4:5] op_sel_hi:[1,0]
	v_pk_mul_f32 v[28:29], v[28:29], v[4:5] op_sel_hi:[1,0]
	v_pk_mul_f32 v[26:27], v[26:27], v[4:5] op_sel_hi:[1,0]
	v_pk_mul_f32 v[24:25], v[24:25], v[4:5] op_sel_hi:[1,0]
	v_pk_mul_f32 v[170:171], v[170:171], v[4:5] op_sel_hi:[1,0]
	v_pk_mul_f32 v[54:55], v[54:55], v[4:5] op_sel_hi:[1,0]
	v_pk_mul_f32 v[52:53], v[52:53], v[4:5] op_sel_hi:[1,0]
	v_pk_mul_f32 v[50:51], v[50:51], v[4:5] op_sel_hi:[1,0]
	v_pk_mul_f32 v[48:49], v[48:49], v[4:5] op_sel_hi:[1,0]
	v_pk_mul_f32 v[46:47], v[46:47], v[4:5] op_sel_hi:[1,0]
	v_pk_mul_f32 v[44:45], v[44:45], v[4:5] op_sel_hi:[1,0]
	v_pk_mul_f32 v[42:43], v[42:43], v[4:5] op_sel_hi:[1,0]
	v_pk_mul_f32 v[40:41], v[40:41], v[4:5] op_sel_hi:[1,0]
	v_pk_mul_f32 v[22:23], v[22:23], v[4:5] op_sel_hi:[1,0]
	v_pk_mul_f32 v[20:21], v[20:21], v[4:5] op_sel_hi:[1,0]
	v_pk_mul_f32 v[18:19], v[18:19], v[4:5] op_sel_hi:[1,0]
	v_pk_mul_f32 v[16:17], v[16:17], v[4:5] op_sel_hi:[1,0]
	v_pk_mul_f32 v[14:15], v[14:15], v[4:5] op_sel_hi:[1,0]
	v_pk_mul_f32 v[12:13], v[12:13], v[4:5] op_sel_hi:[1,0]
	v_pk_mul_f32 v[10:11], v[10:11], v[4:5] op_sel_hi:[1,0]
	v_pk_mul_f32 v[8:9], v[8:9], v[4:5] op_sel_hi:[1,0]
	v_sub_f32_e32 v4, v224, v211
	v_sub_f32_e32 v89, v89, v6
	v_sub_f32_e32 v105, v105, v6
	v_sub_f32_e32 v90, v90, v6
	v_sub_f32_e32 v106, v106, v6
	v_sub_f32_e32 v91, v91, v6
	v_sub_f32_e32 v107, v107, v6
	v_sub_f32_e32 v92, v92, v6
	v_sub_f32_e32 v108, v108, v6
	v_sub_f32_e32 v93, v93, v6
	v_sub_f32_e32 v109, v109, v6
	v_sub_f32_e32 v94, v94, v6
	v_sub_f32_e32 v110, v110, v6
	v_sub_f32_e32 v95, v95, v6
	v_sub_f32_e32 v111, v111, v6
	v_sub_f32_e32 v96, v96, v6
	v_sub_f32_e32 v112, v112, v6
	v_sub_f32_e32 v97, v97, v6
	v_sub_f32_e32 v113, v113, v6
	v_sub_f32_e32 v98, v98, v6
	v_sub_f32_e32 v114, v114, v6
	v_sub_f32_e32 v99, v99, v6
	v_sub_f32_e32 v115, v115, v6
	v_sub_f32_e32 v100, v100, v6
	v_sub_f32_e32 v116, v116, v6
	v_sub_f32_e32 v101, v101, v6
	v_sub_f32_e32 v117, v117, v6
	v_sub_f32_e32 v102, v102, v6
	v_sub_f32_e32 v118, v118, v6
	v_sub_f32_e32 v103, v103, v6
	v_sub_f32_e32 v119, v119, v6
	v_bfe_u32 v6, v4, 16, 1
	v_add3_u32 v6, v4, v6, s45
	v_lshrrev_b32_e32 v7, 16, v6
	v_and_b32_e32 v6, 0xffff0000, v6
	v_sub_f32_e32 v4, v4, v6
	v_bfe_u32 v6, v4, 16, 1
	v_add3_u32 v4, v4, v6, s45
	v_and_or_b32 v4, v4, s92, v7
	v_cndmask_b32_e64 v4, 0, v4, s[6:7]
	v_mov_b32_e32 v6, v5
	v_mov_b32_e32 v7, v5
	s_nop 1
	v_mfma_f32_32x32x16_bf16 v[72:87], v[144:147], v[4:7], 0
	v_exp_f32_e32 v4, v88
	v_exp_f32_e32 v6, v89
	s_nop 0
	v_add_f32_e32 v7, v4, v6
	v_cvt_pk_bf16_f32 v152, v4, v6
	v_exp_f32_e32 v6, v90
	v_exp_f32_e32 v4, v91
	s_nop 0
	v_pk_add_f32 v[88:89], v[6:7], v[4:5]
	v_cvt_pk_bf16_f32 v153, v6, v4
	v_exp_f32_e32 v4, v92
	v_exp_f32_e32 v6, v93
	v_pk_add_f32 v[88:89], v[88:89], v[88:89] op_sel_hi:[0,1]
	v_exp_f32_e32 v88, v95
	v_add_f32_e32 v7, v4, v6
	v_cvt_pk_bf16_f32 v154, v4, v6
	v_exp_f32_e32 v6, v94
	v_exp_f32_e32 v4, v96
	v_pk_add_f32 v[90:91], v[6:7], v[88:89]
	v_cvt_pk_bf16_f32 v155, v6, v88
	v_exp_f32_e32 v6, v97
	v_pk_add_f32 v[90:91], v[90:91], v[90:91] op_sel_hi:[0,1]
	v_exp_f32_e32 v90, v99
	v_add_f32_e32 v7, v4, v6
	v_cvt_pk_bf16_f32 v156, v4, v6
	v_exp_f32_e32 v6, v98
	v_exp_f32_e32 v4, v100
	v_pk_add_f32 v[88:89], v[6:7], v[90:91]
	v_cvt_pk_bf16_f32 v157, v6, v90
	v_exp_f32_e32 v6, v101
	v_pk_add_f32 v[88:89], v[88:89], v[88:89] op_sel_hi:[0,1]
	v_exp_f32_e32 v88, v103
	v_add_f32_e32 v7, v4, v6
	v_cvt_pk_bf16_f32 v158, v4, v6
	v_exp_f32_e32 v6, v102
	v_exp_f32_e32 v4, v104
	v_pk_add_f32 v[90:91], v[6:7], v[88:89]
	v_cvt_pk_bf16_f32 v159, v6, v88
	v_exp_f32_e32 v6, v105
	v_pk_add_f32 v[90:91], v[90:91], v[90:91] op_sel_hi:[0,1]
	v_exp_f32_e32 v90, v107
	v_add_f32_e32 v7, v4, v6
	v_cvt_pk_bf16_f32 v160, v4, v6
	v_exp_f32_e32 v6, v106
	v_exp_f32_e32 v4, v108
	v_pk_add_f32 v[88:89], v[6:7], v[90:91]
	v_cvt_pk_bf16_f32 v161, v6, v90
	v_exp_f32_e32 v6, v109
	v_pk_add_f32 v[88:89], v[88:89], v[88:89] op_sel_hi:[0,1]
	v_exp_f32_e32 v88, v111
	v_add_f32_e32 v7, v4, v6
	v_cvt_pk_bf16_f32 v162, v4, v6
	v_exp_f32_e32 v6, v110
	v_exp_f32_e32 v4, v112
	v_pk_add_f32 v[90:91], v[6:7], v[88:89]
	v_cvt_pk_bf16_f32 v163, v6, v88
	v_exp_f32_e32 v6, v113
	v_pk_add_f32 v[90:91], v[90:91], v[90:91] op_sel_hi:[0,1]
	v_exp_f32_e32 v90, v115
	v_add_f32_e32 v7, v4, v6
	v_cvt_pk_bf16_f32 v164, v4, v6
	v_exp_f32_e32 v6, v114
	v_exp_f32_e32 v4, v116
	v_pk_add_f32 v[88:89], v[6:7], v[90:91]
	v_cvt_pk_bf16_f32 v165, v6, v90
	v_exp_f32_e32 v6, v117
	v_pk_add_f32 v[88:89], v[88:89], v[88:89] op_sel_hi:[0,1]
	v_exp_f32_e32 v88, v119
	v_add_f32_e32 v7, v4, v6
	v_cvt_pk_bf16_f32 v166, v4, v6
	v_exp_f32_e32 v6, v118
	s_nop 0
	v_pk_add_f32 v[90:91], v[6:7], v[88:89]
	s_nop 0
	v_add_f32_e32 v4, v90, v91
	v_cvt_pk_bf16_f32 v167, v6, v88

; DI unsigned pk2(float lo, float hi) { f32x2 v = {lo, hi}; b16x2 r = __builtin_convertvector(v, b16x2); return __builtin_bit_cast(unsigned, r); }
; template <int MODE>
; DI void attn_item(const Params& p, int layer, int bh, int qb, char* lds) {
;     ...
;         auto smpass = [&]() {
;           ps = 0.f;
; #pragma unroll
;           for (int sub = 0; sub < 2; ++sub)
; #pragma unroll
;             for (int ks = 0; ks < 2; ++ks)
; #pragma unroll
;               for (int i = 0; i < 4; ++i) {
;                 const float p0 = __builtin_amdgcn_exp2f(s[sub][8 * ks + 2 * i]), p1 = __builtin_amdgcn_exp2f(s[sub][8 * ks + 2 * i + 1]);
;                 ps += p0 + p1; pk[mp][sub][ks][i] = pk2(p0, p1);
;               }
;         };
;         if (first) rebase();
;         smpass();
;         if (!first && __any(!(ps <= PSLIM))) { rebase(); smpass(); }
;         l[mp] += ps;
.LBB0_477:
	s_or_b64 exec, exec, s[26:27]
	s_nop 2
	v_add_f32_e32 v223, v170, v4
	v_exp_f32_e32 v236, v88
	v_exp_f32_e32 v237, v89
	v_exp_f32_e32 v196, v90
	v_exp_f32_e32 v4, v91
	v_exp_f32_e32 v238, v92
	v_exp_f32_e32 v239, v93
	v_exp_f32_e32 v198, v94
	v_add_f32_e32 v189, v236, v238
	v_exp_f32_e32 v200, v95
	v_add_f32_e32 v7, v237, v239
	v_exp_f32_e32 v232, v96
	v_add_f32_e32 v173, v196, v198
	v_exp_f32_e32 v233, v97
	v_add_f32_e32 v175, v4, v200
	v_exp_f32_e32 v188, v98
	v_add_f32_e32 v189, v189, v232
	v_exp_f32_e32 v190, v99
	v_add_f32_e32 v7, v7, v233
	v_exp_f32_e32 v234, v100
	v_add_f32_e32 v173, v173, v188
	v_exp_f32_e32 v235, v101
	v_add_f32_e32 v175, v175, v190
	v_exp_f32_e32 v192, v102
	v_add_f32_e32 v189, v189, v234
	v_exp_f32_e32 v194, v103
	v_add_f32_e32 v7, v7, v235
	v_exp_f32_e32 v228, v104
	v_add_f32_e32 v173, v173, v192
	v_exp_f32_e32 v229, v105
	v_add_f32_e32 v175, v175, v194
	v_exp_f32_e32 v178, v106
	v_add_f32_e32 v189, v189, v228
	v_exp_f32_e32 v180, v107
	v_add_f32_e32 v7, v7, v229
	v_exp_f32_e32 v230, v108
	v_add_f32_e32 v173, v173, v178
	v_exp_f32_e32 v231, v109
	v_add_f32_e32 v175, v175, v180
	v_exp_f32_e32 v182, v110
	v_add_f32_e32 v189, v189, v230
	v_exp_f32_e32 v186, v111
	v_add_f32_e32 v7, v7, v231
	v_exp_f32_e32 v170, v112
	v_add_f32_e32 v173, v173, v182
	v_exp_f32_e32 v225, v113
	v_add_f32_e32 v175, v175, v186
	v_exp_f32_e32 v6, v114
	v_add_f32_e32 v189, v189, v170
	v_exp_f32_e32 v172, v115
	v_add_f32_e32 v7, v7, v225
	v_exp_f32_e32 v226, v116
	v_add_f32_e32 v173, v173, v6
	v_exp_f32_e32 v227, v117
	v_add_f32_e32 v175, v175, v172
	v_exp_f32_e32 v174, v118
	v_add_f32_e32 v189, v189, v226
	v_exp_f32_e32 v176, v119
	v_add_f32_e32 v7, v7, v227
	s_nop 0
	s_nop 0
	v_add_f32_e32 v173, v173, v174
	v_add_f32_e32 v175, v175, v176
	v_add_f32_e32 v7, v7, v173
	v_add_f32_e32 v189, v189, v175
	v_add_f32_e32 v189, v189, v7
	v_cmp_nge_f32_e32 vcc, s94, v189
	s_cbranch_vccz .LBB0_479
; DI unsigned pk2(float lo, float hi) { f32x2 v = {lo, hi}; b16x2 r = __builtin_convertvector(v, b16x2); return __builtin_bit_cast(unsigned, r); }
; template <int MODE>
; DI void attn_item(const Params& p, int layer, int bh, int qb, char* lds) {
;     ...
;         auto rebase = [&]() {
;           float mx = fmaxf(fmaxf(s[0][0], s[0][1]), s[0][2]);
; #pragma unroll
;           for (int r = 3; r < 15; r += 2) mx = fmaxf(fmaxf(mx, s[0][r]), s[0][r + 1]);
;           mx = fmaxf(mx, s[0][15]);
; #pragma unroll
;           for (int r = 0; r < 16; r += 2) mx = fmaxf(fmaxf(mx, s[1][r]), s[1][r + 1]);
;           const float rm = xchg_max(mx);
;           float delta = first ? rm : fmaxf(rm, 0.f);
;           if (delta < -1e29f) delta = 0.f;
;           m += delta;
;           const float alpha = __builtin_amdgcn_exp2f(-delta);
; #pragma unroll
;           for (int mq = 0; mq < NMAP; ++mq) {
;             l[mq] *= alpha;
; #pragma unroll
;             for (int r = 0; r < 16; ++r) { O[mq][0][r] *= alpha; O[mq][1][r] *= alpha; }
;           }
; #pragma unroll
;           for (int r = 0; r < 16; ++r) { s[0][r] -= delta; s[1][r] -= delta; }
;           set_c0(cb - m);
;         };
;         float ps;
;         auto smpass = [&]() {
;           ps = 0.f;
; #pragma unroll
;           for (int sub = 0; sub < 2; ++sub)
; #pragma unroll
;             for (int ks = 0; ks < 2; ++ks)
; #pragma unroll
;               for (int i = 0; i < 4; ++i) {
;                 const float p0 = __builtin_amdgcn_exp2f(s[sub][8 * ks + 2 * i]), p1 = __builtin_amdgcn_exp2f(s[sub][8 * ks + 2 * i + 1]);
;                 ps += p0 + p1; pk[mp][sub][ks][i] = pk2(p0, p1);
;               }
;         };
;         if (first) rebase();
;         smpass();
;         if (!first && __any(!(ps <= PSLIM))) { rebase(); smpass(); }
	v_max_f32_e32 v4, v89, v89
	v_max_f32_e32 v6, v88, v88
	v_max_f32_e32 v4, v6, v4
	v_max3_f32 v4, v4, v90, v91
	v_max3_f32 v4, v4, v92, v93
	v_max3_f32 v4, v4, v94, v95
	v_max3_f32 v4, v4, v96, v97
	v_max3_f32 v4, v4, v98, v99
	v_max3_f32 v4, v4, v100, v101
	v_max3_f32 v4, v4, v102, v103
	v_max3_f32 v4, v4, v104, v105
	v_max3_f32 v4, v4, v106, v107
	v_max3_f32 v4, v4, v108, v109
	v_max3_f32 v4, v4, v110, v111
	v_max3_f32 v4, v4, v112, v113
	v_max3_f32 v4, v4, v114, v115
	v_max3_f32 v4, v4, v116, v117
	v_max3_f32 v4, v4, v118, v119
	v_mov_b32_e32 v6, v4
	s_nop 1
	v_permlane32_swap_b32_e32 v4, v6
	v_max3_f32 v6, v4, v6, 0
	v_exp_f32_e64 v4, -v6
	v_add_f32_e32 v211, v211, v6
	v_sub_f32_e32 v88, v88, v6
	v_sub_f32_e32 v104, v104, v6
	v_mul_f32_e32 v223, v223, v4
	v_pk_mul_f32 v[70:71], v[70:71], v[4:5] op_sel_hi:[1,0]
	v_pk_mul_f32 v[68:69], v[68:69], v[4:5] op_sel_hi:[1,0]
	v_pk_mul_f32 v[66:67], v[66:67], v[4:5] op_sel_hi:[1,0]
	v_pk_mul_f32 v[64:65], v[64:65], v[4:5] op_sel_hi:[1,0]
	v_pk_mul_f32 v[62:63], v[62:63], v[4:5] op_sel_hi:[1,0]
	v_pk_mul_f32 v[60:61], v[60:61], v[4:5] op_sel_hi:[1,0]
	v_pk_mul_f32 v[58:59], v[58:59], v[4:5] op_sel_hi:[1,0]
	v_pk_mul_f32 v[56:57], v[56:57], v[4:5] op_sel_hi:[1,0]
	v_pk_mul_f32 v[38:39], v[38:39], v[4:5] op_sel_hi:[1,0]
	v_pk_mul_f32 v[36:37], v[36:37], v[4:5] op_sel_hi:[1,0]
	v_pk_mul_f32 v[34:35], v[34:35], v[4:5] op_sel_hi:[1,0]
	v_pk_mul_f32 v[32:33], v[32:33], v[4:5] op_sel_hi:[1,0]
	v_pk_mul_f32 v[30:31], v[30:31], v[4:5] op_sel_hi:[1,0]
	v_pk_mul_f32 v[28:29], v[28:29], v[4:5] op_sel_hi:[1,0]
	v_pk_mul_f32 v[26:27], v[26:27], v[4:5] op_sel_hi:[1,0]
	v_pk_mul_f32 v[24:25], v[24:25], v[4:5] op_sel_hi:[1,0]
	v_mul_f32_e32 v171, v171, v4
	v_pk_mul_f32 v[54:55], v[54:55], v[4:5] op_sel_hi:[1,0]
	v_pk_mul_f32 v[52:53], v[52:53], v[4:5] op_sel_hi:[1,0]
	v_pk_mul_f32 v[50:51], v[50:51], v[4:5] op_sel_hi:[1,0]
	v_pk_mul_f32 v[48:49], v[48:49], v[4:5] op_sel_hi:[1,0]
	v_pk_mul_f32 v[46:47], v[46:47], v[4:5] op_sel_hi:[1,0]
	v_pk_mul_f32 v[44:45], v[44:45], v[4:5] op_sel_hi:[1,0]
	v_pk_mul_f32 v[42:43], v[42:43], v[4:5] op_sel_hi:[1,0]
	v_pk_mul_f32 v[40:41], v[40:41], v[4:5] op_sel_hi:[1,0]
	v_pk_mul_f32 v[22:23], v[22:23], v[4:5] op_sel_hi:[1,0]
	v_pk_mul_f32 v[20:21], v[20:21], v[4:5] op_sel_hi:[1,0]
	v_pk_mul_f32 v[18:19], v[18:19], v[4:5] op_sel_hi:[1,0]
	v_pk_mul_f32 v[16:17], v[16:17], v[4:5] op_sel_hi:[1,0]
	v_pk_mul_f32 v[14:15], v[14:15], v[4:5] op_sel_hi:[1,0]
	v_pk_mul_f32 v[12:13], v[12:13], v[4:5] op_sel_hi:[1,0]
	v_pk_mul_f32 v[10:11], v[10:11], v[4:5] op_sel_hi:[1,0]
	v_pk_mul_f32 v[8:9], v[8:9], v[4:5] op_sel_hi:[1,0]
	v_sub_f32_e32 v4, v224, v211
	v_sub_f32_e32 v89, v89, v6
	v_sub_f32_e32 v105, v105, v6
	v_sub_f32_e32 v90, v90, v6
	v_sub_f32_e32 v106, v106, v6
	v_sub_f32_e32 v91, v91, v6
	v_sub_f32_e32 v107, v107, v6
	v_sub_f32_e32 v170, v92, v6
	v_sub_f32_e32 v108, v108, v6
	v_sub_f32_e32 v172, v93, v6
	v_sub_f32_e32 v109, v109, v6
	v_sub_f32_e32 v94, v94, v6
	v_sub_f32_e32 v110, v110, v6
	v_sub_f32_e32 v95, v95, v6
	v_sub_f32_e32 v111, v111, v6
	v_sub_f32_e32 v96, v96, v6
	v_sub_f32_e32 v112, v112, v6
	v_sub_f32_e32 v97, v97, v6
	v_sub_f32_e32 v113, v113, v6
	v_sub_f32_e32 v98, v98, v6
	v_sub_f32_e32 v114, v114, v6
	v_sub_f32_e32 v99, v99, v6
	v_sub_f32_e32 v115, v115, v6
	v_sub_f32_e32 v100, v100, v6
	v_sub_f32_e32 v116, v116, v6
	v_sub_f32_e32 v101, v101, v6
	v_sub_f32_e32 v117, v117, v6
	v_sub_f32_e32 v102, v102, v6
	v_sub_f32_e32 v118, v118, v6
	v_sub_f32_e32 v103, v103, v6
	v_sub_f32_e32 v119, v119, v6
	v_bfe_u32 v6, v4, 16, 1
	v_add3_u32 v6, v4, v6, s45
	v_lshrrev_b32_e32 v7, 16, v6
	v_and_b32_e32 v6, 0xffff0000, v6
	v_sub_f32_e32 v4, v4, v6
	v_bfe_u32 v6, v4, 16, 1
	v_add3_u32 v4, v4, v6, s45
	v_and_or_b32 v4, v4, s92, v7
	v_cndmask_b32_e64 v4, 0, v4, s[6:7]
	v_mov_b32_e32 v6, v5
	v_mov_b32_e32 v7, v5
	s_nop 1
	v_mfma_f32_32x32x16_bf16 v[72:87], v[144:147], v[4:7], 0
	v_exp_f32_e32 v4, v88
	v_exp_f32_e32 v6, v89
	s_nop 0
	v_add_f32_e32 v7, v4, v6
	v_cvt_pk_bf16_f32 v88, v4, v6
	v_exp_f32_e32 v6, v90
	v_exp_f32_e32 v4, v91
	s_nop 0
	v_pk_add_f32 v[90:91], v[6:7], v[4:5]
	v_cvt_pk_bf16_f32 v89, v6, v4
	v_exp_f32_e32 v4, v170
	v_exp_f32_e32 v6, v172
	v_pk_add_f32 v[92:93], v[90:91], v[90:91] op_sel_hi:[0,1]
	v_exp_f32_e32 v92, v95
	v_add_f32_e32 v7, v4, v6
	v_cvt_pk_bf16_f32 v90, v4, v6
	v_exp_f32_e32 v6, v94
	v_exp_f32_e32 v4, v96
	v_pk_add_f32 v[94:95], v[6:7], v[92:93]
	v_cvt_pk_bf16_f32 v91, v6, v92
	v_exp_f32_e32 v6, v97
	v_pk_add_f32 v[94:95], v[94:95], v[94:95] op_sel_hi:[0,1]
	v_exp_f32_e32 v94, v99
	v_add_f32_e32 v7, v4, v6
	v_cvt_pk_bf16_f32 v92, v4, v6
	v_exp_f32_e32 v6, v98
	v_exp_f32_e32 v4, v100
	v_pk_add_f32 v[96:97], v[6:7], v[94:95]
	v_cvt_pk_bf16_f32 v93, v6, v94
	v_exp_f32_e32 v6, v101
	v_pk_add_f32 v[96:97], v[96:97], v[96:97] op_sel_hi:[0,1]
	v_exp_f32_e32 v96, v103
	v_add_f32_e32 v7, v4, v6
	v_cvt_pk_bf16_f32 v94, v4, v6
	v_exp_f32_e32 v6, v102
	v_exp_f32_e32 v4, v104
	v_pk_add_f32 v[98:99], v[6:7], v[96:97]
	v_cvt_pk_bf16_f32 v95, v6, v96
	v_exp_f32_e32 v6, v105
	v_pk_add_f32 v[98:99], v[98:99], v[98:99] op_sel_hi:[0,1]
	v_exp_f32_e32 v98, v107
	v_add_f32_e32 v7, v4, v6
	v_cvt_pk_bf16_f32 v96, v4, v6
	v_exp_f32_e32 v6, v106
	v_exp_f32_e32 v4, v108
	v_pk_add_f32 v[100:101], v[6:7], v[98:99]
	v_cvt_pk_bf16_f32 v97, v6, v98
	v_exp_f32_e32 v6, v109
	v_pk_add_f32 v[100:101], v[100:101], v[100:101] op_sel_hi:[0,1]
	v_exp_f32_e32 v100, v111
	v_add_f32_e32 v7, v4, v6
	v_cvt_pk_bf16_f32 v98, v4, v6
	v_exp_f32_e32 v6, v110
	v_exp_f32_e32 v4, v112
	v_pk_add_f32 v[102:103], v[6:7], v[100:101]
	v_cvt_pk_bf16_f32 v99, v6, v100
	v_exp_f32_e32 v6, v113
	v_pk_add_f32 v[102:103], v[102:103], v[102:103] op_sel_hi:[0,1]
	v_exp_f32_e32 v102, v115
	v_add_f32_e32 v7, v4, v6
	v_cvt_pk_bf16_f32 v100, v4, v6
	v_exp_f32_e32 v6, v114
	v_exp_f32_e32 v4, v116
	v_pk_add_f32 v[104:105], v[6:7], v[102:103]
	v_cvt_pk_bf16_f32 v101, v6, v102
	v_exp_f32_e32 v6, v117
	v_pk_add_f32 v[104:105], v[104:105], v[104:105] op_sel_hi:[0,1]
	v_exp_f32_e32 v104, v119
	v_add_f32_e32 v7, v4, v6
	v_cvt_pk_bf16_f32 v102, v4, v6
	v_exp_f32_e32 v6, v118
	s_nop 0
	v_pk_add_f32 v[106:107], v[6:7], v[104:105]
	s_nop 0
	v_add_f32_e32 v189, v106, v107
	v_cvt_pk_bf16_f32 v103, v6, v104
	s_branch .LBB0_480

; DI unsigned pk2(float lo, float hi) { f32x2 v = {lo, hi}; b16x2 r = __builtin_convertvector(v, b16x2); return __builtin_bit_cast(unsigned, r); }
; template <int MODE>
; DI void attn_item(const Params& p, int layer, int bh, int qb, char* lds) {
;     ...
;         auto smpass = [&]() {
;           ps = 0.f;
; #pragma unroll
;           for (int sub = 0; sub < 2; ++sub)
; #pragma unroll
;             for (int ks = 0; ks < 2; ++ks)
; #pragma unroll
;               for (int i = 0; i < 4; ++i) {
;                 const float p0 = __builtin_amdgcn_exp2f(s[sub][8 * ks + 2 * i]), p1 = __builtin_amdgcn_exp2f(s[sub][8 * ks + 2 * i + 1]);
;                 ps += p0 + p1; pk[mp][sub][ks][i] = pk2(p0, p1);
;               }
;         };
;         if (first) rebase();
;         smpass();
;         if (!first && __any(!(ps <= PSLIM))) { rebase(); smpass(); }
;         l[mp] += ps;
.LBB0_494:
	s_or_b64 exec, exec, s[26:27]
	s_nop 2
	v_add_f32_e32 v222, v171, v189
	v_exp_f32_e32 v152, v88
	v_exp_f32_e32 v153, v89
	v_exp_f32_e32 v6, v90
	v_exp_f32_e32 v4, v91
	v_exp_f32_e32 v158, v94
	v_exp_f32_e32 v162, v98
	v_exp_f32_e32 v166, v102
	v_add_f32_e32 v7, v152, v158
	v_exp_f32_e32 v154, v92
	v_add_f32_e32 v171, v153, v162
	v_exp_f32_e32 v155, v93
	v_add_f32_e32 v187, v6, v166
	v_exp_f32_e32 v156, v95
	v_add_f32_e32 v188, v4, v154
	v_exp_f32_e32 v174, v106
	v_add_f32_e32 v7, v7, v155
	v_exp_f32_e32 v178, v110
	v_add_f32_e32 v171, v171, v156
	v_exp_f32_e32 v157, v96
	v_add_f32_e32 v187, v187, v174
	v_exp_f32_e32 v159, v97
	v_add_f32_e32 v188, v188, v178
	v_exp_f32_e32 v160, v99
	v_add_f32_e32 v7, v7, v157
	v_exp_f32_e32 v182, v114
	v_add_f32_e32 v171, v171, v159
	v_exp_f32_e32 v170, v118
	v_add_f32_e32 v187, v187, v160
	v_exp_f32_e32 v161, v100
	v_add_f32_e32 v188, v188, v182
	v_exp_f32_e32 v163, v101
	v_add_f32_e32 v7, v7, v170
	v_exp_f32_e32 v164, v103
	v_add_f32_e32 v171, v171, v161
	v_exp_f32_e32 v165, v104
	v_add_f32_e32 v187, v187, v163
	v_exp_f32_e32 v167, v105
	v_add_f32_e32 v188, v188, v164
	v_exp_f32_e32 v172, v107
	v_add_f32_e32 v7, v7, v165
	v_exp_f32_e32 v173, v108
	v_add_f32_e32 v171, v171, v167
	v_exp_f32_e32 v175, v109
	v_add_f32_e32 v187, v187, v172
	v_exp_f32_e32 v176, v111
	v_add_f32_e32 v188, v188, v173
	v_exp_f32_e32 v177, v112
	v_add_f32_e32 v7, v7, v175
	v_exp_f32_e32 v179, v113
	v_add_f32_e32 v171, v171, v176
	v_exp_f32_e32 v180, v115
	v_add_f32_e32 v187, v187, v177
	v_exp_f32_e32 v181, v116
	v_add_f32_e32 v188, v188, v179
	v_exp_f32_e32 v183, v117
	v_add_f32_e32 v7, v7, v180
	v_exp_f32_e32 v186, v119
	v_add_f32_e32 v171, v171, v181
	s_nop 0
	s_nop 0
	v_add_f32_e32 v187, v187, v183
	v_add_f32_e32 v188, v188, v186
	v_add_f32_e32 v171, v171, v187
	v_add_f32_e32 v7, v7, v188
	v_add_f32_e32 v7, v7, v171
	v_cmp_nge_f32_e32 vcc, s94, v7
	s_cbranch_vccz .LBB0_496
; DI unsigned pk2(float lo, float hi) { f32x2 v = {lo, hi}; b16x2 r = __builtin_convertvector(v, b16x2); return __builtin_bit_cast(unsigned, r); }
; template <int MODE>
; DI void attn_item(const Params& p, int layer, int bh, int qb, char* lds) {
;     ...
;         auto rebase = [&]() {
;           float mx = fmaxf(fmaxf(s[0][0], s[0][1]), s[0][2]);
; #pragma unroll
;           for (int r = 3; r < 15; r += 2) mx = fmaxf(fmaxf(mx, s[0][r]), s[0][r + 1]);
;           mx = fmaxf(mx, s[0][15]);
; #pragma unroll
;           for (int r = 0; r < 16; r += 2) mx = fmaxf(fmaxf(mx, s[1][r]), s[1][r + 1]);
;           const float rm = xchg_max(mx);
;           float delta = first ? rm : fmaxf(rm, 0.f);
;           if (delta < -1e29f) delta = 0.f;
;           m += delta;
;           const float alpha = __builtin_amdgcn_exp2f(-delta);
; #pragma unroll
;           for (int mq = 0; mq < NMAP; ++mq) {
;             l[mq] *= alpha;
; #pragma unroll
;             for (int r = 0; r < 16; ++r) { O[mq][0][r] *= alpha; O[mq][1][r] *= alpha; }
;           }
; #pragma unroll
;           for (int r = 0; r < 16; ++r) { s[0][r] -= delta; s[1][r] -= delta; }
;           set_c0(cb - m);
;         };
;         float ps;
;         auto smpass = [&]() {
;           ps = 0.f;
; #pragma unroll
;           for (int sub = 0; sub < 2; ++sub)
; #pragma unroll
;             for (int ks = 0; ks < 2; ++ks)
; #pragma unroll
;               for (int i = 0; i < 4; ++i) {
;                 const float p0 = __builtin_amdgcn_exp2f(s[sub][8 * ks + 2 * i]), p1 = __builtin_amdgcn_exp2f(s[sub][8 * ks + 2 * i + 1]);
;                 ps += p0 + p1; pk[mp][sub][ks][i] = pk2(p0, p1);
;               }
;         };
;         if (first) rebase();
;         smpass();
;         if (!first && __any(!(ps <= PSLIM))) { rebase(); smpass(); }
	v_max_f32_e32 v4, v89, v89
	v_max_f32_e32 v6, v88, v88
	v_max_f32_e32 v4, v6, v4
	v_max3_f32 v4, v4, v90, v91
	v_max3_f32 v4, v4, v92, v93
	v_max3_f32 v4, v4, v94, v95
	v_max3_f32 v4, v4, v96, v97
	v_max3_f32 v4, v4, v98, v99
	v_max3_f32 v4, v4, v100, v101
	v_max3_f32 v4, v4, v102, v103
	v_max3_f32 v4, v4, v104, v105
	v_max3_f32 v4, v4, v106, v107
	v_max3_f32 v4, v4, v108, v109
	v_max3_f32 v4, v4, v110, v111
	v_max3_f32 v4, v4, v112, v113
	v_max3_f32 v4, v4, v114, v115
	v_max3_f32 v4, v4, v116, v117
	v_max3_f32 v4, v4, v118, v119
	v_mov_b32_e32 v6, v4
	s_nop 1
	v_permlane32_swap_b32_e32 v4, v6
	v_max3_f32 v6, v4, v6, 0
	v_exp_f32_e64 v4, -v6
	v_add_f32_e32 v211, v211, v6
	v_sub_f32_e32 v88, v88, v6
	v_sub_f32_e32 v104, v104, v6
	v_mul_f32_e32 v223, v223, v4
	v_pk_mul_f32 v[70:71], v[70:71], v[4:5] op_sel_hi:[1,0]
	v_pk_mul_f32 v[68:69], v[68:69], v[4:5] op_sel_hi:[1,0]
	v_pk_mul_f32 v[66:67], v[66:67], v[4:5] op_sel_hi:[1,0]
	v_pk_mul_f32 v[64:65], v[64:65], v[4:5] op_sel_hi:[1,0]
	v_pk_mul_f32 v[62:63], v[62:63], v[4:5] op_sel_hi:[1,0]
	v_pk_mul_f32 v[60:61], v[60:61], v[4:5] op_sel_hi:[1,0]
	v_pk_mul_f32 v[58:59], v[58:59], v[4:5] op_sel_hi:[1,0]
	v_pk_mul_f32 v[56:57], v[56:57], v[4:5] op_sel_hi:[1,0]
	v_pk_mul_f32 v[38:39], v[38:39], v[4:5] op_sel_hi:[1,0]
	v_pk_mul_f32 v[36:37], v[36:37], v[4:5] op_sel_hi:[1,0]
	v_pk_mul_f32 v[34:35], v[34:35], v[4:5] op_sel_hi:[1,0]
	v_pk_mul_f32 v[32:33], v[32:33], v[4:5] op_sel_hi:[1,0]
	v_pk_mul_f32 v[30:31], v[30:31], v[4:5] op_sel_hi:[1,0]
	v_pk_mul_f32 v[28:29], v[28:29], v[4:5] op_sel_hi:[1,0]
	v_pk_mul_f32 v[26:27], v[26:27], v[4:5] op_sel_hi:[1,0]
	v_pk_mul_f32 v[24:25], v[24:25], v[4:5] op_sel_hi:[1,0]
	v_mul_f32_e32 v222, v222, v4
	v_pk_mul_f32 v[54:55], v[54:55], v[4:5] op_sel_hi:[1,0]
	v_pk_mul_f32 v[52:53], v[52:53], v[4:5] op_sel_hi:[1,0]
	v_pk_mul_f32 v[50:51], v[50:51], v[4:5] op_sel_hi:[1,0]
	v_pk_mul_f32 v[48:49], v[48:49], v[4:5] op_sel_hi:[1,0]
	v_pk_mul_f32 v[46:47], v[46:47], v[4:5] op_sel_hi:[1,0]
	v_pk_mul_f32 v[44:45], v[44:45], v[4:5] op_sel_hi:[1,0]
	v_pk_mul_f32 v[42:43], v[42:43], v[4:5] op_sel_hi:[1,0]
	v_pk_mul_f32 v[40:41], v[40:41], v[4:5] op_sel_hi:[1,0]
	v_pk_mul_f32 v[22:23], v[22:23], v[4:5] op_sel_hi:[1,0]
	v_pk_mul_f32 v[20:21], v[20:21], v[4:5] op_sel_hi:[1,0]
	v_pk_mul_f32 v[18:19], v[18:19], v[4:5] op_sel_hi:[1,0]
	v_pk_mul_f32 v[16:17], v[16:17], v[4:5] op_sel_hi:[1,0]
	v_pk_mul_f32 v[14:15], v[14:15], v[4:5] op_sel_hi:[1,0]
	v_pk_mul_f32 v[12:13], v[12:13], v[4:5] op_sel_hi:[1,0]
	v_pk_mul_f32 v[10:11], v[10:11], v[4:5] op_sel_hi:[1,0]
	v_pk_mul_f32 v[8:9], v[8:9], v[4:5] op_sel_hi:[1,0]
	v_sub_f32_e32 v4, v224, v211
	v_sub_f32_e32 v89, v89, v6
	v_sub_f32_e32 v105, v105, v6
	v_sub_f32_e32 v90, v90, v6
	v_sub_f32_e32 v106, v106, v6
	v_sub_f32_e32 v91, v91, v6
	v_sub_f32_e32 v107, v107, v6
	v_sub_f32_e32 v92, v92, v6
	v_sub_f32_e32 v108, v108, v6
	v_sub_f32_e32 v93, v93, v6
	v_sub_f32_e32 v109, v109, v6
	v_sub_f32_e32 v94, v94, v6
	v_sub_f32_e32 v110, v110, v6
	v_sub_f32_e32 v95, v95, v6
	v_sub_f32_e32 v111, v111, v6
	v_sub_f32_e32 v96, v96, v6
	v_sub_f32_e32 v112, v112, v6
	v_sub_f32_e32 v97, v97, v6
	v_sub_f32_e32 v113, v113, v6
	v_sub_f32_e32 v98, v98, v6
	v_sub_f32_e32 v114, v114, v6
	v_sub_f32_e32 v99, v99, v6
	v_sub_f32_e32 v115, v115, v6
	v_sub_f32_e32 v100, v100, v6
	v_sub_f32_e32 v116, v116, v6
	v_sub_f32_e32 v101, v101, v6
	v_sub_f32_e32 v117, v117, v6
	v_sub_f32_e32 v102, v102, v6
	v_sub_f32_e32 v118, v118, v6
	v_sub_f32_e32 v103, v103, v6
	v_sub_f32_e32 v119, v119, v6
	v_bfe_u32 v6, v4, 16, 1
	v_add3_u32 v6, v4, v6, s45
	v_lshrrev_b32_e32 v7, 16, v6
	v_and_b32_e32 v6, 0xffff0000, v6
	v_sub_f32_e32 v4, v4, v6
	v_bfe_u32 v6, v4, 16, 1
	v_add3_u32 v4, v4, v6, s45
	v_and_or_b32 v4, v4, s92, v7
	v_cndmask_b32_e64 v4, 0, v4, s[6:7]
	v_mov_b32_e32 v6, v5
	v_mov_b32_e32 v7, v5
	s_nop 1
	v_mfma_f32_32x32x16_bf16 v[72:87], v[144:147], v[4:7], 0
	v_exp_f32_e32 v4, v88
	v_exp_f32_e32 v6, v89
	s_nop 0
	v_add_f32_e32 v7, v4, v6
	v_cvt_pk_bf16_f32 v152, v4, v6
	v_exp_f32_e32 v6, v90
	v_exp_f32_e32 v4, v91
	s_nop 0
	v_pk_add_f32 v[88:89], v[6:7], v[4:5]
	v_cvt_pk_bf16_f32 v153, v6, v4
	v_exp_f32_e32 v4, v92
	v_exp_f32_e32 v6, v93
	v_pk_add_f32 v[88:89], v[88:89], v[88:89] op_sel_hi:[0,1]
	v_exp_f32_e32 v88, v95
	v_add_f32_e32 v7, v4, v6
	v_cvt_pk_bf16_f32 v154, v4, v6
	v_exp_f32_e32 v6, v94
	v_exp_f32_e32 v4, v96
	v_pk_add_f32 v[90:91], v[6:7], v[88:89]
	v_cvt_pk_bf16_f32 v155, v6, v88
	v_exp_f32_e32 v6, v97
	v_pk_add_f32 v[90:91], v[90:91], v[90:91] op_sel_hi:[0,1]
	v_exp_f32_e32 v90, v99
	v_add_f32_e32 v7, v4, v6
	v_cvt_pk_bf16_f32 v156, v4, v6
	v_exp_f32_e32 v6, v98
	v_exp_f32_e32 v4, v100
	v_pk_add_f32 v[88:89], v[6:7], v[90:91]
	v_cvt_pk_bf16_f32 v157, v6, v90
	v_exp_f32_e32 v6, v101
	v_pk_add_f32 v[88:89], v[88:89], v[88:89] op_sel_hi:[0,1]
	v_exp_f32_e32 v88, v103
	v_add_f32_e32 v7, v4, v6
	v_cvt_pk_bf16_f32 v158, v4, v6
	v_exp_f32_e32 v6, v102
	v_exp_f32_e32 v4, v104
	v_pk_add_f32 v[90:91], v[6:7], v[88:89]
	v_cvt_pk_bf16_f32 v159, v6, v88
	v_exp_f32_e32 v6, v105
	v_pk_add_f32 v[90:91], v[90:91], v[90:91] op_sel_hi:[0,1]
	v_exp_f32_e32 v90, v107
	v_add_f32_e32 v7, v4, v6
	v_cvt_pk_bf16_f32 v160, v4, v6
	v_exp_f32_e32 v6, v106
	v_exp_f32_e32 v4, v108
	v_pk_add_f32 v[88:89], v[6:7], v[90:91]
	v_cvt_pk_bf16_f32 v161, v6, v90
	v_exp_f32_e32 v6, v109
	v_pk_add_f32 v[88:89], v[88:89], v[88:89] op_sel_hi:[0,1]
	v_exp_f32_e32 v88, v111
	v_add_f32_e32 v7, v4, v6
	v_cvt_pk_bf16_f32 v162, v4, v6
	v_exp_f32_e32 v6, v110
	v_exp_f32_e32 v4, v112
	v_pk_add_f32 v[90:91], v[6:7], v[88:89]
	v_cvt_pk_bf16_f32 v163, v6, v88
	v_exp_f32_e32 v6, v113
	v_pk_add_f32 v[90:91], v[90:91], v[90:91] op_sel_hi:[0,1]
	v_exp_f32_e32 v90, v115
	v_add_f32_e32 v7, v4, v6
	v_cvt_pk_bf16_f32 v164, v4, v6
	v_exp_f32_e32 v6, v114
	v_exp_f32_e32 v4, v116
	v_pk_add_f32 v[88:89], v[6:7], v[90:91]
	v_cvt_pk_bf16_f32 v165, v6, v90
	v_exp_f32_e32 v6, v117
	v_pk_add_f32 v[88:89], v[88:89], v[88:89] op_sel_hi:[0,1]
	v_exp_f32_e32 v88, v119
	v_add_f32_e32 v7, v4, v6
	v_cvt_pk_bf16_f32 v166, v4, v6
	v_exp_f32_e32 v6, v118
	s_nop 0
	v_pk_add_f32 v[90:91], v[6:7], v[88:89]
	s_nop 0
	v_add_f32_e32 v7, v90, v91
	v_cvt_pk_bf16_f32 v167, v6, v88
	s_branch .LBB0_497

; DI unsigned pk2(float lo, float hi) { f32x2 v = {lo, hi}; b16x2 r = __builtin_convertvector(v, b16x2); return __builtin_bit_cast(unsigned, r); }
; template <int MODE>
; DI void attn_item(const Params& p, int layer, int bh, int qb, char* lds) {
;     ...
;         auto smpass = [&]() {
;           ps = 0.f;
; #pragma unroll
;           for (int sub = 0; sub < 2; ++sub)
; #pragma unroll
;             for (int ks = 0; ks < 2; ++ks)
; #pragma unroll
;               for (int i = 0; i < 4; ++i) {
;                 const float p0 = __builtin_amdgcn_exp2f(s[sub][8 * ks + 2 * i]), p1 = __builtin_amdgcn_exp2f(s[sub][8 * ks + 2 * i + 1]);
;                 ps += p0 + p1; pk[mp][sub][ks][i] = pk2(p0, p1);
;               }
;         };
;         if (first) rebase();
;         smpass();
;         if (!first && __any(!(ps <= PSLIM))) { rebase(); smpass(); }
;         l[mp] += ps;
.LBB0_499:
	s_or_b64 exec, exec, s[26:27]
	s_nop 2
	v_add_f32_e32 v170, v223, v7
	v_exp_f32_e32 v235, v88
	v_exp_f32_e32 v236, v89
	v_exp_f32_e32 v196, v90
	v_exp_f32_e32 v4, v91
	v_exp_f32_e32 v237, v92
	v_exp_f32_e32 v238, v93
	v_exp_f32_e32 v198, v94
	v_add_f32_e32 v7, v235, v237
	v_exp_f32_e32 v200, v95
	v_add_f32_e32 v173, v236, v238
	v_exp_f32_e32 v231, v96
	v_add_f32_e32 v175, v196, v198
	v_exp_f32_e32 v232, v97
	v_add_f32_e32 v177, v4, v200
	v_exp_f32_e32 v188, v98
	v_add_f32_e32 v7, v7, v231
	v_exp_f32_e32 v190, v99
	v_add_f32_e32 v173, v173, v232
	v_exp_f32_e32 v233, v100
	v_add_f32_e32 v175, v175, v188
	v_exp_f32_e32 v234, v101
	v_add_f32_e32 v177, v177, v190
	v_exp_f32_e32 v192, v102
	v_add_f32_e32 v7, v7, v233
	v_exp_f32_e32 v194, v103
	v_add_f32_e32 v173, v173, v234
	v_exp_f32_e32 v227, v104
	v_add_f32_e32 v175, v175, v192
	v_exp_f32_e32 v228, v105
	v_add_f32_e32 v177, v177, v194
	v_exp_f32_e32 v178, v106
	v_add_f32_e32 v7, v7, v227
	v_exp_f32_e32 v180, v107
	v_add_f32_e32 v173, v173, v228
	v_exp_f32_e32 v229, v108
	v_add_f32_e32 v175, v175, v178
	v_exp_f32_e32 v230, v109
	v_add_f32_e32 v177, v177, v180
	v_exp_f32_e32 v182, v110
	v_add_f32_e32 v7, v7, v229
	v_exp_f32_e32 v186, v111
	v_add_f32_e32 v173, v173, v230
	v_exp_f32_e32 v171, v112
	v_add_f32_e32 v175, v175, v182
	v_exp_f32_e32 v223, v113
	v_add_f32_e32 v177, v177, v186
	v_exp_f32_e32 v6, v114
	v_add_f32_e32 v7, v7, v171
	v_exp_f32_e32 v172, v115
	v_add_f32_e32 v173, v173, v223
	v_exp_f32_e32 v225, v116
	v_add_f32_e32 v175, v175, v6
	v_exp_f32_e32 v226, v117
	v_add_f32_e32 v177, v177, v172
	v_exp_f32_e32 v174, v118
	v_add_f32_e32 v7, v7, v225
	v_exp_f32_e32 v176, v119
	v_add_f32_e32 v173, v173, v226
	s_nop 0
	s_nop 0
	v_add_f32_e32 v175, v175, v174
	v_add_f32_e32 v177, v177, v176
	v_add_f32_e32 v173, v173, v175
	v_add_f32_e32 v7, v7, v177
	v_add_f32_e32 v7, v7, v173
	v_cmp_nge_f32_e32 vcc, s94, v7
	s_cbranch_vccz .LBB0_501
; DI unsigned pk2(float lo, float hi) { f32x2 v = {lo, hi}; b16x2 r = __builtin_convertvector(v, b16x2); return __builtin_bit_cast(unsigned, r); }
; template <int MODE>
; DI void attn_item(const Params& p, int layer, int bh, int qb, char* lds) {
;     ...
;         auto rebase = [&]() {
;           float mx = fmaxf(fmaxf(s[0][0], s[0][1]), s[0][2]);
; #pragma unroll
;           for (int r = 3; r < 15; r += 2) mx = fmaxf(fmaxf(mx, s[0][r]), s[0][r + 1]);
;           mx = fmaxf(mx, s[0][15]);
; #pragma unroll
;           for (int r = 0; r < 16; r += 2) mx = fmaxf(fmaxf(mx, s[1][r]), s[1][r + 1]);
;           const float rm = xchg_max(mx);
;           float delta = first ? rm : fmaxf(rm, 0.f);
;           if (delta < -1e29f) delta = 0.f;
;           m += delta;
;           const float alpha = __builtin_amdgcn_exp2f(-delta);
; #pragma unroll
;           for (int mq = 0; mq < NMAP; ++mq) {
;             l[mq] *= alpha;
; #pragma unroll
;             for (int r = 0; r < 16; ++r) { O[mq][0][r] *= alpha; O[mq][1][r] *= alpha; }
;           }
; #pragma unroll
;           for (int r = 0; r < 16; ++r) { s[0][r] -= delta; s[1][r] -= delta; }
;           set_c0(cb - m);
;         };
;         float ps;
;         auto smpass = [&]() {
;           ps = 0.f;
; #pragma unroll
;           for (int sub = 0; sub < 2; ++sub)
; #pragma unroll
;             for (int ks = 0; ks < 2; ++ks)
; #pragma unroll
;               for (int i = 0; i < 4; ++i) {
;                 const float p0 = __builtin_amdgcn_exp2f(s[sub][8 * ks + 2 * i]), p1 = __builtin_amdgcn_exp2f(s[sub][8 * ks + 2 * i + 1]);
;                 ps += p0 + p1; pk[mp][sub][ks][i] = pk2(p0, p1);
;               }
;         };
;         if (first) rebase();
;         smpass();
;         if (!first && __any(!(ps <= PSLIM))) { rebase(); smpass(); }
	v_max_f32_e32 v4, v89, v89
	v_max_f32_e32 v6, v88, v88
	v_max_f32_e32 v4, v6, v4
	v_max3_f32 v4, v4, v90, v91
	v_max3_f32 v4, v4, v92, v93
	v_max3_f32 v4, v4, v94, v95
	v_max3_f32 v4, v4, v96, v97
	v_max3_f32 v4, v4, v98, v99
	v_max3_f32 v4, v4, v100, v101
	v_max3_f32 v4, v4, v102, v103
	v_max3_f32 v4, v4, v104, v105
	v_max3_f32 v4, v4, v106, v107
	v_max3_f32 v4, v4, v108, v109
	v_max3_f32 v4, v4, v110, v111
	v_max3_f32 v4, v4, v112, v113
	v_max3_f32 v4, v4, v114, v115
	v_max3_f32 v4, v4, v116, v117
	v_max3_f32 v4, v4, v118, v119
	v_mov_b32_e32 v6, v4
	s_nop 1
	v_permlane32_swap_b32_e32 v4, v6
	v_max3_f32 v6, v4, v6, 0
	v_exp_f32_e64 v4, -v6
	v_add_f32_e32 v211, v211, v6
	v_sub_f32_e32 v88, v88, v6
	v_sub_f32_e32 v104, v104, v6
	v_mul_f32_e32 v170, v170, v4
	v_pk_mul_f32 v[70:71], v[70:71], v[4:5] op_sel_hi:[1,0]
	v_pk_mul_f32 v[68:69], v[68:69], v[4:5] op_sel_hi:[1,0]
	v_pk_mul_f32 v[66:67], v[66:67], v[4:5] op_sel_hi:[1,0]
	v_pk_mul_f32 v[64:65], v[64:65], v[4:5] op_sel_hi:[1,0]
	v_pk_mul_f32 v[62:63], v[62:63], v[4:5] op_sel_hi:[1,0]
	v_pk_mul_f32 v[60:61], v[60:61], v[4:5] op_sel_hi:[1,0]
	v_pk_mul_f32 v[58:59], v[58:59], v[4:5] op_sel_hi:[1,0]
	v_pk_mul_f32 v[56:57], v[56:57], v[4:5] op_sel_hi:[1,0]
	v_pk_mul_f32 v[38:39], v[38:39], v[4:5] op_sel_hi:[1,0]
	v_pk_mul_f32 v[36:37], v[36:37], v[4:5] op_sel_hi:[1,0]
	v_pk_mul_f32 v[34:35], v[34:35], v[4:5] op_sel_hi:[1,0]
	v_pk_mul_f32 v[32:33], v[32:33], v[4:5] op_sel_hi:[1,0]
	v_pk_mul_f32 v[30:31], v[30:31], v[4:5] op_sel_hi:[1,0]
	v_pk_mul_f32 v[28:29], v[28:29], v[4:5] op_sel_hi:[1,0]
	v_pk_mul_f32 v[26:27], v[26:27], v[4:5] op_sel_hi:[1,0]
	v_pk_mul_f32 v[24:25], v[24:25], v[4:5] op_sel_hi:[1,0]
	v_mul_f32_e32 v222, v222, v4
	v_pk_mul_f32 v[54:55], v[54:55], v[4:5] op_sel_hi:[1,0]
	v_pk_mul_f32 v[52:53], v[52:53], v[4:5] op_sel_hi:[1,0]
	v_pk_mul_f32 v[50:51], v[50:51], v[4:5] op_sel_hi:[1,0]
	v_pk_mul_f32 v[48:49], v[48:49], v[4:5] op_sel_hi:[1,0]
	v_pk_mul_f32 v[46:47], v[46:47], v[4:5] op_sel_hi:[1,0]
	v_pk_mul_f32 v[44:45], v[44:45], v[4:5] op_sel_hi:[1,0]
	v_pk_mul_f32 v[42:43], v[42:43], v[4:5] op_sel_hi:[1,0]
	v_pk_mul_f32 v[40:41], v[40:41], v[4:5] op_sel_hi:[1,0]
	v_pk_mul_f32 v[22:23], v[22:23], v[4:5] op_sel_hi:[1,0]
	v_pk_mul_f32 v[20:21], v[20:21], v[4:5] op_sel_hi:[1,0]
	v_pk_mul_f32 v[18:19], v[18:19], v[4:5] op_sel_hi:[1,0]
	v_pk_mul_f32 v[16:17], v[16:17], v[4:5] op_sel_hi:[1,0]
	v_pk_mul_f32 v[14:15], v[14:15], v[4:5] op_sel_hi:[1,0]
	v_pk_mul_f32 v[12:13], v[12:13], v[4:5] op_sel_hi:[1,0]
	v_pk_mul_f32 v[10:11], v[10:11], v[4:5] op_sel_hi:[1,0]
	v_pk_mul_f32 v[8:9], v[8:9], v[4:5] op_sel_hi:[1,0]
	v_sub_f32_e32 v4, v224, v211
	v_sub_f32_e32 v89, v89, v6
	v_sub_f32_e32 v105, v105, v6
	v_sub_f32_e32 v90, v90, v6
	v_sub_f32_e32 v106, v106, v6
	v_sub_f32_e32 v91, v91, v6
	v_sub_f32_e32 v107, v107, v6
	v_sub_f32_e32 v171, v92, v6
	v_sub_f32_e32 v108, v108, v6
	v_sub_f32_e32 v172, v93, v6
	v_sub_f32_e32 v109, v109, v6
	v_sub_f32_e32 v94, v94, v6
	v_sub_f32_e32 v110, v110, v6
	v_sub_f32_e32 v95, v95, v6
	v_sub_f32_e32 v111, v111, v6
	v_sub_f32_e32 v96, v96, v6
	v_sub_f32_e32 v112, v112, v6
	v_sub_f32_e32 v97, v97, v6
	v_sub_f32_e32 v113, v113, v6
	v_sub_f32_e32 v98, v98, v6
	v_sub_f32_e32 v114, v114, v6
	v_sub_f32_e32 v99, v99, v6
	v_sub_f32_e32 v115, v115, v6
	v_sub_f32_e32 v100, v100, v6
	v_sub_f32_e32 v116, v116, v6
	v_sub_f32_e32 v101, v101, v6
	v_sub_f32_e32 v117, v117, v6
	v_sub_f32_e32 v102, v102, v6
	v_sub_f32_e32 v118, v118, v6
	v_sub_f32_e32 v103, v103, v6
	v_sub_f32_e32 v119, v119, v6
	v_bfe_u32 v6, v4, 16, 1
	v_add3_u32 v6, v4, v6, s45
	v_lshrrev_b32_e32 v7, 16, v6
	v_and_b32_e32 v6, 0xffff0000, v6
	v_sub_f32_e32 v4, v4, v6
	v_bfe_u32 v6, v4, 16, 1
	v_add3_u32 v4, v4, v6, s45
	v_and_or_b32 v4, v4, s92, v7
	v_cndmask_b32_e64 v4, 0, v4, s[6:7]
	v_mov_b32_e32 v6, v5
	v_mov_b32_e32 v7, v5
	s_nop 1
	v_mfma_f32_32x32x16_bf16 v[72:87], v[144:147], v[4:7], 0
	v_exp_f32_e32 v4, v88
	v_exp_f32_e32 v6, v89
	s_nop 0
	v_add_f32_e32 v7, v4, v6
	v_cvt_pk_bf16_f32 v88, v4, v6
	v_exp_f32_e32 v6, v90
	v_exp_f32_e32 v4, v91
	s_nop 0
	v_pk_add_f32 v[90:91], v[6:7], v[4:5]
	v_cvt_pk_bf16_f32 v89, v6, v4
	v_exp_f32_e32 v4, v171
	v_exp_f32_e32 v6, v172
	v_pk_add_f32 v[92:93], v[90:91], v[90:91] op_sel_hi:[0,1]
	v_exp_f32_e32 v92, v95
	v_add_f32_e32 v7, v4, v6
	v_cvt_pk_bf16_f32 v90, v4, v6
	v_exp_f32_e32 v6, v94
	v_exp_f32_e32 v4, v96
	v_pk_add_f32 v[94:95], v[6:7], v[92:93]
	v_cvt_pk_bf16_f32 v91, v6, v92
	v_exp_f32_e32 v6, v97
	v_pk_add_f32 v[94:95], v[94:95], v[94:95] op_sel_hi:[0,1]
	v_exp_f32_e32 v94, v99
	v_add_f32_e32 v7, v4, v6
	v_cvt_pk_bf16_f32 v92, v4, v6
	v_exp_f32_e32 v6, v98
	v_exp_f32_e32 v4, v100
	v_pk_add_f32 v[96:97], v[6:7], v[94:95]
	v_cvt_pk_bf16_f32 v93, v6, v94
	v_exp_f32_e32 v6, v101
	v_pk_add_f32 v[96:97], v[96:97], v[96:97] op_sel_hi:[0,1]
	v_exp_f32_e32 v96, v103
	v_add_f32_e32 v7, v4, v6
	v_cvt_pk_bf16_f32 v94, v4, v6
	v_exp_f32_e32 v6, v102
	v_exp_f32_e32 v4, v104
	v_pk_add_f32 v[98:99], v[6:7], v[96:97]
	v_cvt_pk_bf16_f32 v95, v6, v96
	v_exp_f32_e32 v6, v105
	v_pk_add_f32 v[98:99], v[98:99], v[98:99] op_sel_hi:[0,1]
	v_exp_f32_e32 v98, v107
	v_add_f32_e32 v7, v4, v6
	v_cvt_pk_bf16_f32 v96, v4, v6
	v_exp_f32_e32 v6, v106
	v_exp_f32_e32 v4, v108
	v_pk_add_f32 v[100:101], v[6:7], v[98:99]
	v_cvt_pk_bf16_f32 v97, v6, v98
	v_exp_f32_e32 v6, v109
	v_pk_add_f32 v[100:101], v[100:101], v[100:101] op_sel_hi:[0,1]
	v_exp_f32_e32 v100, v111
	v_add_f32_e32 v7, v4, v6
	v_cvt_pk_bf16_f32 v98, v4, v6
	v_exp_f32_e32 v6, v110
	v_exp_f32_e32 v4, v112
	v_pk_add_f32 v[102:103], v[6:7], v[100:101]
	v_cvt_pk_bf16_f32 v99, v6, v100
	v_exp_f32_e32 v6, v113
	v_pk_add_f32 v[102:103], v[102:103], v[102:103] op_sel_hi:[0,1]
	v_exp_f32_e32 v102, v115
	v_add_f32_e32 v7, v4, v6
	v_cvt_pk_bf16_f32 v100, v4, v6
	v_exp_f32_e32 v6, v114
	v_exp_f32_e32 v4, v116
	v_pk_add_f32 v[104:105], v[6:7], v[102:103]
	v_cvt_pk_bf16_f32 v101, v6, v102
	v_exp_f32_e32 v6, v117
	v_pk_add_f32 v[104:105], v[104:105], v[104:105] op_sel_hi:[0,1]
	v_exp_f32_e32 v104, v119
	v_add_f32_e32 v7, v4, v6
	v_cvt_pk_bf16_f32 v102, v4, v6
	v_exp_f32_e32 v6, v118
	s_nop 0
	v_pk_add_f32 v[106:107], v[6:7], v[104:105]
	s_nop 0
	v_add_f32_e32 v7, v106, v107
	v_cvt_pk_bf16_f32 v103, v6, v104
	s_branch .LBB0_502
